# prologue rebalanced: the 24 workgroups with w_in bias items take 5 of their 9 norm rows, the other 768 rows go one each to waves 0-3 of workgroups 24-215; workgroups without a bias item skip bias_phas
# speedup vs baseline: 1.0189x; 1.0042x over previous
.LBB0_112:
	s_or_b64 exec, exec, s[0:1]
	s_mov_b64 s[4:5], s[34:35]
	s_mov_b64 s[8:9], s[34:35]
	s_mov_b64 s[10:11], s[34:35]
	s_waitcnt lgkmcnt(0)
	v_mov_b32_e32 v1, v0
	s_barrier
	s_nop 0
	v_readfirstlane_b32 s0, v1
	s_ashr_i32 s6, s0, 6
	s_add_i32 s0, s6, s90
	s_cmpk_gt_i32 s0, 0x47ff
	s_cbranch_scc1 .LBB0_117
	v_and_b32_e32 v2, 63, v1
	v_mbcnt_lo_u32_b32 v1, -1, 0
	v_mbcnt_hi_u32_b32 v3, -1, v1
	v_and_b32_e32 v1, 64, v3
	v_add_u32_e32 v4, 64, v1
	v_xor_b32_e32 v1, 1, v3
	v_cmp_lt_i32_e32 vcc, v1, v4
	v_xor_b32_e32 v5, 2, v3
	s_ashr_i32 s7, s6, 31
	v_cndmask_b32_e32 v1, v3, v1, vcc
	v_cmp_lt_i32_e32 vcc, v5, v4
	s_ashr_i32 s12, s90, 31
	s_add_u32 s6, s6, s90
	v_cndmask_b32_e32 v5, v3, v5, vcc
	v_lshlrev_b32_e32 v24, 2, v5
	v_xor_b32_e32 v5, 4, v3
	v_cmp_lt_i32_e32 vcc, v5, v4
	s_addc_u32 s7, s7, s12
	s_lshl_b64 s[12:13], s[6:7], 11
	v_cndmask_b32_e32 v5, v3, v5, vcc
	v_lshlrev_b32_e32 v25, 2, v5
	v_xor_b32_e32 v5, 8, v3
	v_cmp_lt_i32_e32 vcc, v5, v4
	v_mov_b32_e32 v19, 0
	v_lshlrev_b32_e32 v18, 4, v2
	v_cndmask_b32_e32 v5, v3, v5, vcc
	v_lshlrev_b32_e32 v26, 2, v5
	v_xor_b32_e32 v5, 16, v3
	v_cmp_lt_i32_e32 vcc, v5, v4
	s_add_u32 s8, s8, s12
	v_lshl_add_u64 v[20:21], s[28:29], 0, v[18:19]
	v_cndmask_b32_e32 v5, v3, v5, vcc
	v_lshlrev_b32_e32 v27, 2, v5
	v_xor_b32_e32 v5, 32, v3
	v_cmp_lt_i32_e32 vcc, v5, v4
	v_lshlrev_b32_e32 v18, 3, v2
	s_addc_u32 s9, s9, s13
	v_cndmask_b32_e32 v3, v3, v5, vcc
	v_lshl_add_u64 v[4:5], s[8:9], 0, v[18:19]
	s_mov_b64 s[8:9], 0x3500400
	s_ashr_i32 s19, s18, 31
	v_lshl_add_u64 v[22:23], v[4:5], 0, s[8:9]
	s_lshl_b64 s[8:9], s[18:19], 11
	s_lshl_b64 s[12:13], s[6:7], 2
	s_add_u32 s10, s10, s12
	s_addc_u32 s11, s11, s13
	s_add_u32 s10, s10, 0xb6000
	v_lshlrev_b32_e32 v1, 2, v1
	v_lshlrev_b32_e32 v28, 2, v3
	v_cmp_eq_u32_e64 s[0:1], 0, v2
	s_addc_u32 s11, s11, 0
	s_lshl_b64 s[14:15], s[18:19], 2
	v_lshlrev_b32_e32 v18, 4, v2
	s_mov_b64 s[26:27], 0x11000
	s_mov_b32 s12, 0x11000
	s_movk_i32 s13, 0x7fff
	s_mov_b32 s22, 0xffff0000
	s_cmpk_lg_i32 s18, 0x800
	s_cbranch_scc1 .LBB0_115
	s_cmpk_lg_i32 s94, 0x100
	s_cbranch_scc1 .LBB0_115
	v_lshrrev_b32_e32 v112, 1, v18
	s_lshl_b64 s[12:13], s[6:7], 12
	s_add_u32 s14, s16, s12
	s_addc_u32 s15, s17, s13
	s_add_u32 s36, s20, s12
	s_addc_u32 s37, s21, s13
	s_lshl_b64 s[12:13], s[6:7], 11
	s_add_u32 s8, s34, s12
	s_addc_u32 s9, s35, s13
	s_add_u32 s8, s8, 0x3500000
	s_addc_u32 s9, s9, 0
	s_add_u32 s26, s34, 0x11000
	s_addc_u32 s27, s35, 0
	s_movk_i32 s98, 9
	s_cmpk_lt_u32 s90, 0xc0
	s_cselect_b32 s98, 5, s98
	s_sub_u32 s99, s6, s90
	s_cmpk_lt_u32 s99, 4
	s_cselect_b32 s100, 1, 0
	s_cmpk_lt_u32 s90, 0x6c0
	s_cselect_b32 s101, 1, 0
	s_and_b32 s100, s100, s101
	s_cmpk_ge_u32 s90, 0xc0
	s_cselect_b32 s101, 1, 0
	s_and_b32 s100, s100, s101
	s_add_u32 s98, s98, s100
	s_sub_u32 s101, s90, 0xc0
	s_lshr_b32 s101, s101, 1
	s_add_u32 s99, s99, s101
	s_mul_hi_u32 s100, s99, 0x1555556
	s_mul_i32 s101, s100, 0xc0
	s_sub_u32 s99, s99, s101
	s_add_u32 s100, s100, 5
	global_load_dwordx4 v[32:35], v[20:21], off
	global_load_dwordx4 v[36:39], v[20:21], off offset:1024
	global_load_dwordx4 v[40:43], v[20:21], off offset:2048
	global_load_dwordx4 v[44:47], v[20:21], off offset:3072
	global_load_dwordx4 v[48:51], v18, s[14:15] nt
	global_load_dwordx4 v[52:55], v18, s[14:15] offset:1024 nt
	global_load_dwordx4 v[56:59], v18, s[14:15] offset:2048 nt
	global_load_dwordx4 v[60:63], v18, s[14:15] offset:3072 nt
	global_load_dwordx4 v[80:83], v18, s[26:27]
	global_load_dwordx4 v[84:87], v18, s[26:27] offset:1024
	global_load_dwordx4 v[88:91], v18, s[26:27] offset:2048
	global_load_dwordx4 v[92:95], v18, s[26:27] offset:3072
	s_add_u32 s14, s14, 0x800000
	s_addc_u32 s15, s15, 0
	s_add_u32 s26, s26, 0x6000
	s_addc_u32 s27, s27, 0
	global_load_dwordx4 v[64:67], v18, s[14:15] nt
	global_load_dwordx4 v[68:71], v18, s[14:15] offset:1024 nt
	global_load_dwordx4 v[72:75], v18, s[14:15] offset:2048 nt
	global_load_dwordx4 v[76:79], v18, s[14:15] offset:3072 nt
	global_load_dwordx4 v[96:99], v18, s[26:27]
	global_load_dwordx4 v[100:103], v18, s[26:27] offset:1024
	global_load_dwordx4 v[104:107], v18, s[26:27] offset:2048
	global_load_dwordx4 v[108:111], v18, s[26:27] offset:3072
	s_waitcnt vmcnt(8)
	v_mul_f32_e32 v29, v49, v49
	v_mul_f32_e32 v30, v51, v51
	v_mul_f32_e32 v31, v53, v53
	v_mul_f32_e32 v113, v55, v55
	v_mul_f32_e32 v114, v57, v57
	v_mul_f32_e32 v115, v59, v59
	v_mul_f32_e32 v116, v61, v61
	v_mul_f32_e32 v117, v63, v63
	v_fmac_f32_e32 v29, v48, v48
	v_fmac_f32_e32 v30, v50, v50
	v_fmac_f32_e32 v31, v52, v52
	v_fmac_f32_e32 v113, v54, v54
	v_fmac_f32_e32 v114, v56, v56
	v_fmac_f32_e32 v115, v58, v58
	v_fmac_f32_e32 v116, v60, v60
	v_fmac_f32_e32 v117, v62, v62
	v_add_f32_e32 v29, v29, v30
	v_add_f32_e32 v31, v31, v113
	v_add_f32_e32 v114, v114, v115
	v_add_f32_e32 v116, v116, v117
	v_add_f32_e32 v29, v29, v31
	v_add_f32_e32 v29, v29, v114
	v_add_f32_e32 v29, v29, v116
	ds_bpermute_b32 v30, v1, v29
	v_mul_f32_e32 v48, v48, v32
	v_mul_f32_e32 v49, v49, v33
	v_mul_f32_e32 v50, v50, v34
	v_mul_f32_e32 v51, v51, v35
	v_mul_f32_e32 v52, v52, v36
	v_mul_f32_e32 v53, v53, v37
	v_mul_f32_e32 v54, v54, v38
	v_mul_f32_e32 v55, v55, v39
	s_waitcnt lgkmcnt(0)
	v_add_f32_e32 v29, v29, v30
	ds_bpermute_b32 v30, v24, v29
	v_mul_f32_e32 v56, v56, v40
	v_mul_f32_e32 v57, v57, v41
	v_mul_f32_e32 v58, v58, v42
	v_mul_f32_e32 v59, v59, v43
	v_mul_f32_e32 v60, v60, v44
	v_mul_f32_e32 v61, v61, v45
	v_mul_f32_e32 v62, v62, v46
	v_mul_f32_e32 v63, v63, v47
	s_waitcnt lgkmcnt(0)
	v_add_f32_e32 v29, v29, v30
	ds_bpermute_b32 v30, v25, v29
	v_add_f32_e32 v80, 1.0, v80
	v_add_f32_e32 v81, 1.0, v81
	v_add_f32_e32 v82, 1.0, v82
	v_add_f32_e32 v83, 1.0, v83
	v_add_f32_e32 v84, 1.0, v84
	v_add_f32_e32 v85, 1.0, v85
	v_add_f32_e32 v86, 1.0, v86
	v_add_f32_e32 v87, 1.0, v87
	s_waitcnt lgkmcnt(0)
	v_add_f32_e32 v29, v29, v30
	ds_bpermute_b32 v30, v26, v29
	v_add_f32_e32 v88, 1.0, v88
	v_add_f32_e32 v89, 1.0, v89
	v_add_f32_e32 v90, 1.0, v90
	v_add_f32_e32 v91, 1.0, v91
	v_add_f32_e32 v92, 1.0, v92
	v_add_f32_e32 v93, 1.0, v93
	v_add_f32_e32 v94, 1.0, v94
	v_add_f32_e32 v95, 1.0, v95
	s_waitcnt lgkmcnt(0)
	v_add_f32_e32 v29, v29, v30
	ds_bpermute_b32 v30, v27, v29
	v_mul_f32_e32 v48, v48, v80
	v_mul_f32_e32 v49, v49, v81
	v_mul_f32_e32 v50, v50, v82
	v_mul_f32_e32 v51, v51, v83
	v_mul_f32_e32 v52, v52, v84
	v_mul_f32_e32 v53, v53, v85
	v_mul_f32_e32 v54, v54, v86
	v_mul_f32_e32 v55, v55, v87
	s_waitcnt lgkmcnt(0)
	v_add_f32_e32 v29, v29, v30
	ds_bpermute_b32 v30, v28, v29
	v_mul_f32_e32 v56, v56, v88
	v_mul_f32_e32 v57, v57, v89
	v_mul_f32_e32 v58, v58, v90
	v_mul_f32_e32 v59, v59, v91
	v_mul_f32_e32 v60, v60, v92
	v_mul_f32_e32 v61, v61, v93
	v_mul_f32_e32 v62, v62, v94
	v_mul_f32_e32 v63, v63, v95
	s_waitcnt lgkmcnt(0)
	v_add_f32_e32 v29, v29, v30
	s_mov_b64 s[22:23], exec
	s_mov_b64 exec, s[0:1]
	global_store_dword v19, v29, s[10:11]
	s_mov_b64 exec, s[22:23]
	v_cvt_pk_bf16_f32 v2, v48, v49
	v_cvt_pk_bf16_f32 v3, v50, v51
	v_cvt_pk_bf16_f32 v4, v52, v53
	v_cvt_pk_bf16_f32 v5, v54, v55
	v_cvt_pk_bf16_f32 v6, v56, v57
	v_cvt_pk_bf16_f32 v7, v58, v59
	v_cvt_pk_bf16_f32 v8, v60, v61
	v_cvt_pk_bf16_f32 v9, v62, v63
	global_store_dwordx2 v112, v[2:3], s[8:9]
	global_store_dwordx2 v112, v[4:5], s[8:9] offset:512
	global_store_dwordx2 v112, v[6:7], s[8:9] offset:1024
	global_store_dwordx2 v112, v[8:9], s[8:9] offset:1536
	s_add_u32 s10, s10, 0x2000
	s_addc_u32 s11, s11, 0
	s_add_u32 s8, s8, 0x400000
	s_addc_u32 s9, s9, 0
	s_add_u32 s14, s14, 0x800000
	s_addc_u32 s15, s15, 0
	s_add_u32 s26, s26, 0x6000
	s_addc_u32 s27, s27, 0
	global_load_dwordx4 v[48:51], v18, s[14:15] nt
	global_load_dwordx4 v[52:55], v18, s[14:15] offset:1024 nt
	global_load_dwordx4 v[56:59], v18, s[14:15] offset:2048 nt
	global_load_dwordx4 v[60:63], v18, s[14:15] offset:3072 nt
	global_load_dwordx4 v[80:83], v18, s[26:27]
	global_load_dwordx4 v[84:87], v18, s[26:27] offset:1024
	global_load_dwordx4 v[88:91], v18, s[26:27] offset:2048
	global_load_dwordx4 v[92:95], v18, s[26:27] offset:3072
	s_waitcnt vmcnt(13)
	v_mul_f32_e32 v29, v65, v65
	v_mul_f32_e32 v30, v67, v67
	v_mul_f32_e32 v31, v69, v69
	v_mul_f32_e32 v113, v71, v71
	v_mul_f32_e32 v114, v73, v73
	v_mul_f32_e32 v115, v75, v75
	v_mul_f32_e32 v116, v77, v77
	v_mul_f32_e32 v117, v79, v79
	v_fmac_f32_e32 v29, v64, v64
	v_fmac_f32_e32 v30, v66, v66
	v_fmac_f32_e32 v31, v68, v68
	v_fmac_f32_e32 v113, v70, v70
	v_fmac_f32_e32 v114, v72, v72
	v_fmac_f32_e32 v115, v74, v74
	v_fmac_f32_e32 v116, v76, v76
	v_fmac_f32_e32 v117, v78, v78
	v_add_f32_e32 v29, v29, v30
	v_add_f32_e32 v31, v31, v113
	v_add_f32_e32 v114, v114, v115
	v_add_f32_e32 v116, v116, v117
	v_add_f32_e32 v29, v29, v31
	v_add_f32_e32 v29, v29, v114
	v_add_f32_e32 v29, v29, v116
	ds_bpermute_b32 v30, v1, v29
	v_mul_f32_e32 v64, v64, v32
	v_mul_f32_e32 v65, v65, v33
	v_mul_f32_e32 v66, v66, v34
	v_mul_f32_e32 v67, v67, v35
	v_mul_f32_e32 v68, v68, v36
	v_mul_f32_e32 v69, v69, v37
	v_mul_f32_e32 v70, v70, v38
	v_mul_f32_e32 v71, v71, v39
	s_waitcnt lgkmcnt(0)
	v_add_f32_e32 v29, v29, v30
	ds_bpermute_b32 v30, v24, v29
	v_mul_f32_e32 v72, v72, v40
	v_mul_f32_e32 v73, v73, v41
	v_mul_f32_e32 v74, v74, v42
	v_mul_f32_e32 v75, v75, v43
	v_mul_f32_e32 v76, v76, v44
	v_mul_f32_e32 v77, v77, v45
	v_mul_f32_e32 v78, v78, v46
	v_mul_f32_e32 v79, v79, v47
	s_waitcnt lgkmcnt(0)
	v_add_f32_e32 v29, v29, v30
	ds_bpermute_b32 v30, v25, v29
	v_add_f32_e32 v96, 1.0, v96
	v_add_f32_e32 v97, 1.0, v97
	v_add_f32_e32 v98, 1.0, v98
	v_add_f32_e32 v99, 1.0, v99
	v_add_f32_e32 v100, 1.0, v100
	v_add_f32_e32 v101, 1.0, v101
	v_add_f32_e32 v102, 1.0, v102
	v_add_f32_e32 v103, 1.0, v103
	s_waitcnt lgkmcnt(0)
	v_add_f32_e32 v29, v29, v30
	ds_bpermute_b32 v30, v26, v29
	v_add_f32_e32 v104, 1.0, v104
	v_add_f32_e32 v105, 1.0, v105
	v_add_f32_e32 v106, 1.0, v106
	v_add_f32_e32 v107, 1.0, v107
	v_add_f32_e32 v108, 1.0, v108
	v_add_f32_e32 v109, 1.0, v109
	v_add_f32_e32 v110, 1.0, v110
	v_add_f32_e32 v111, 1.0, v111
	s_waitcnt lgkmcnt(0)
	v_add_f32_e32 v29, v29, v30
	ds_bpermute_b32 v30, v27, v29
	v_mul_f32_e32 v64, v64, v96
	v_mul_f32_e32 v65, v65, v97
	v_mul_f32_e32 v66, v66, v98
	v_mul_f32_e32 v67, v67, v99
	v_mul_f32_e32 v68, v68, v100
	v_mul_f32_e32 v69, v69, v101
	v_mul_f32_e32 v70, v70, v102
	v_mul_f32_e32 v71, v71, v103
	s_waitcnt lgkmcnt(0)
	v_add_f32_e32 v29, v29, v30
	ds_bpermute_b32 v30, v28, v29
	v_mul_f32_e32 v72, v72, v104
	v_mul_f32_e32 v73, v73, v105
	v_mul_f32_e32 v74, v74, v106
	v_mul_f32_e32 v75, v75, v107
	v_mul_f32_e32 v76, v76, v108
	v_mul_f32_e32 v77, v77, v109
	v_mul_f32_e32 v78, v78, v110
	v_mul_f32_e32 v79, v79, v111
	s_waitcnt lgkmcnt(0)
	v_add_f32_e32 v29, v29, v30
	s_mov_b64 s[22:23], exec
	s_mov_b64 exec, s[0:1]
	global_store_dword v19, v29, s[10:11]
	s_mov_b64 exec, s[22:23]
	v_cvt_pk_bf16_f32 v10, v64, v65
	v_cvt_pk_bf16_f32 v11, v66, v67
	v_cvt_pk_bf16_f32 v12, v68, v69
	v_cvt_pk_bf16_f32 v13, v70, v71
	v_cvt_pk_bf16_f32 v14, v72, v73
	v_cvt_pk_bf16_f32 v15, v74, v75
	v_cvt_pk_bf16_f32 v16, v76, v77
	v_cvt_pk_bf16_f32 v17, v78, v79
	global_store_dwordx2 v112, v[10:11], s[8:9]
	global_store_dwordx2 v112, v[12:13], s[8:9] offset:512
	global_store_dwordx2 v112, v[14:15], s[8:9] offset:1024
	global_store_dwordx2 v112, v[16:17], s[8:9] offset:1536
	s_add_u32 s10, s10, 0x2000
	s_addc_u32 s11, s11, 0
	s_add_u32 s8, s8, 0x400000
	s_addc_u32 s9, s9, 0
	s_add_u32 s14, s14, 0x800000
	s_addc_u32 s15, s15, 0
	s_add_u32 s26, s26, 0x6000
	s_addc_u32 s27, s27, 0
	global_load_dwordx4 v[64:67], v18, s[14:15] nt
	global_load_dwordx4 v[68:71], v18, s[14:15] offset:1024 nt
	global_load_dwordx4 v[72:75], v18, s[14:15] offset:2048 nt
	global_load_dwordx4 v[76:79], v18, s[14:15] offset:3072 nt
	global_load_dwordx4 v[96:99], v18, s[26:27]
	global_load_dwordx4 v[100:103], v18, s[26:27] offset:1024
	global_load_dwordx4 v[104:107], v18, s[26:27] offset:2048
	global_load_dwordx4 v[108:111], v18, s[26:27] offset:3072
	s_waitcnt vmcnt(13)
	v_mul_f32_e32 v29, v49, v49
	v_mul_f32_e32 v30, v51, v51
	v_mul_f32_e32 v31, v53, v53
	v_mul_f32_e32 v113, v55, v55
	v_mul_f32_e32 v114, v57, v57
	v_mul_f32_e32 v115, v59, v59
	v_mul_f32_e32 v116, v61, v61
	v_mul_f32_e32 v117, v63, v63
	v_fmac_f32_e32 v29, v48, v48
	v_fmac_f32_e32 v30, v50, v50
	v_fmac_f32_e32 v31, v52, v52
	v_fmac_f32_e32 v113, v54, v54
	v_fmac_f32_e32 v114, v56, v56
	v_fmac_f32_e32 v115, v58, v58
	v_fmac_f32_e32 v116, v60, v60
	v_fmac_f32_e32 v117, v62, v62
	v_add_f32_e32 v29, v29, v30
	v_add_f32_e32 v31, v31, v113
	v_add_f32_e32 v114, v114, v115
	v_add_f32_e32 v116, v116, v117
	v_add_f32_e32 v29, v29, v31
	v_add_f32_e32 v29, v29, v114
	v_add_f32_e32 v29, v29, v116
	ds_bpermute_b32 v30, v1, v29
	v_mul_f32_e32 v48, v48, v32
	v_mul_f32_e32 v49, v49, v33
	v_mul_f32_e32 v50, v50, v34
	v_mul_f32_e32 v51, v51, v35
	v_mul_f32_e32 v52, v52, v36
	v_mul_f32_e32 v53, v53, v37
	v_mul_f32_e32 v54, v54, v38
	v_mul_f32_e32 v55, v55, v39
	s_waitcnt lgkmcnt(0)
	v_add_f32_e32 v29, v29, v30
	ds_bpermute_b32 v30, v24, v29
	v_mul_f32_e32 v56, v56, v40
	v_mul_f32_e32 v57, v57, v41
	v_mul_f32_e32 v58, v58, v42
	v_mul_f32_e32 v59, v59, v43
	v_mul_f32_e32 v60, v60, v44
	v_mul_f32_e32 v61, v61, v45
	v_mul_f32_e32 v62, v62, v46
	v_mul_f32_e32 v63, v63, v47
	s_waitcnt lgkmcnt(0)
	v_add_f32_e32 v29, v29, v30
	ds_bpermute_b32 v30, v25, v29
	v_add_f32_e32 v80, 1.0, v80
	v_add_f32_e32 v81, 1.0, v81
	v_add_f32_e32 v82, 1.0, v82
	v_add_f32_e32 v83, 1.0, v83
	v_add_f32_e32 v84, 1.0, v84
	v_add_f32_e32 v85, 1.0, v85
	v_add_f32_e32 v86, 1.0, v86
	v_add_f32_e32 v87, 1.0, v87
	s_waitcnt lgkmcnt(0)
	v_add_f32_e32 v29, v29, v30
	ds_bpermute_b32 v30, v26, v29
	v_add_f32_e32 v88, 1.0, v88
	v_add_f32_e32 v89, 1.0, v89
	v_add_f32_e32 v90, 1.0, v90
	v_add_f32_e32 v91, 1.0, v91
	v_add_f32_e32 v92, 1.0, v92
	v_add_f32_e32 v93, 1.0, v93
	v_add_f32_e32 v94, 1.0, v94
	v_add_f32_e32 v95, 1.0, v95
	s_waitcnt lgkmcnt(0)
	v_add_f32_e32 v29, v29, v30
	ds_bpermute_b32 v30, v27, v29
	v_mul_f32_e32 v48, v48, v80
	v_mul_f32_e32 v49, v49, v81
	v_mul_f32_e32 v50, v50, v82
	v_mul_f32_e32 v51, v51, v83
	v_mul_f32_e32 v52, v52, v84
	v_mul_f32_e32 v53, v53, v85
	v_mul_f32_e32 v54, v54, v86
	v_mul_f32_e32 v55, v55, v87
	s_waitcnt lgkmcnt(0)
	v_add_f32_e32 v29, v29, v30
	ds_bpermute_b32 v30, v28, v29
	v_mul_f32_e32 v56, v56, v88
	v_mul_f32_e32 v57, v57, v89
	v_mul_f32_e32 v58, v58, v90
	v_mul_f32_e32 v59, v59, v91
	v_mul_f32_e32 v60, v60, v92
	v_mul_f32_e32 v61, v61, v93
	v_mul_f32_e32 v62, v62, v94
	v_mul_f32_e32 v63, v63, v95
	s_waitcnt lgkmcnt(0)
	v_add_f32_e32 v29, v29, v30
	s_mov_b64 s[22:23], exec
	s_mov_b64 exec, s[0:1]
	global_store_dword v19, v29, s[10:11]
	s_mov_b64 exec, s[22:23]
	v_cvt_pk_bf16_f32 v2, v48, v49
	v_cvt_pk_bf16_f32 v3, v50, v51
	v_cvt_pk_bf16_f32 v4, v52, v53
	v_cvt_pk_bf16_f32 v5, v54, v55
	v_cvt_pk_bf16_f32 v6, v56, v57
	v_cvt_pk_bf16_f32 v7, v58, v59
	v_cvt_pk_bf16_f32 v8, v60, v61
	v_cvt_pk_bf16_f32 v9, v62, v63
	global_store_dwordx2 v112, v[2:3], s[8:9]
	global_store_dwordx2 v112, v[4:5], s[8:9] offset:512
	global_store_dwordx2 v112, v[6:7], s[8:9] offset:1024
	global_store_dwordx2 v112, v[8:9], s[8:9] offset:1536
	s_add_u32 s10, s10, 0x2000
	s_addc_u32 s11, s11, 0
	s_add_u32 s8, s8, 0x400000
	s_addc_u32 s9, s9, 0
	s_add_u32 s14, s14, 0x800000
	s_addc_u32 s15, s15, 0
	s_add_u32 s26, s26, 0x6000
	s_addc_u32 s27, s27, 0
	global_load_dwordx4 v[48:51], v18, s[14:15] nt
	global_load_dwordx4 v[52:55], v18, s[14:15] offset:1024 nt
	global_load_dwordx4 v[56:59], v18, s[14:15] offset:2048 nt
	global_load_dwordx4 v[60:63], v18, s[14:15] offset:3072 nt
	global_load_dwordx4 v[80:83], v18, s[26:27]
	global_load_dwordx4 v[84:87], v18, s[26:27] offset:1024
	global_load_dwordx4 v[88:91], v18, s[26:27] offset:2048
	global_load_dwordx4 v[92:95], v18, s[26:27] offset:3072
	s_waitcnt vmcnt(13)
	v_mul_f32_e32 v29, v65, v65
	v_mul_f32_e32 v30, v67, v67
	v_mul_f32_e32 v31, v69, v69
	v_mul_f32_e32 v113, v71, v71
	v_mul_f32_e32 v114, v73, v73
	v_mul_f32_e32 v115, v75, v75
	v_mul_f32_e32 v116, v77, v77
	v_mul_f32_e32 v117, v79, v79
	v_fmac_f32_e32 v29, v64, v64
	v_fmac_f32_e32 v30, v66, v66
	v_fmac_f32_e32 v31, v68, v68
	v_fmac_f32_e32 v113, v70, v70
	v_fmac_f32_e32 v114, v72, v72
	v_fmac_f32_e32 v115, v74, v74
	v_fmac_f32_e32 v116, v76, v76
	v_fmac_f32_e32 v117, v78, v78
	v_add_f32_e32 v29, v29, v30
	v_add_f32_e32 v31, v31, v113
	v_add_f32_e32 v114, v114, v115
	v_add_f32_e32 v116, v116, v117
	v_add_f32_e32 v29, v29, v31
	v_add_f32_e32 v29, v29, v114
	v_add_f32_e32 v29, v29, v116
	ds_bpermute_b32 v30, v1, v29
	v_mul_f32_e32 v64, v64, v32
	v_mul_f32_e32 v65, v65, v33
	v_mul_f32_e32 v66, v66, v34
	v_mul_f32_e32 v67, v67, v35
	v_mul_f32_e32 v68, v68, v36
	v_mul_f32_e32 v69, v69, v37
	v_mul_f32_e32 v70, v70, v38
	v_mul_f32_e32 v71, v71, v39
	s_waitcnt lgkmcnt(0)
	v_add_f32_e32 v29, v29, v30
	ds_bpermute_b32 v30, v24, v29
	v_mul_f32_e32 v72, v72, v40
	v_mul_f32_e32 v73, v73, v41
	v_mul_f32_e32 v74, v74, v42
	v_mul_f32_e32 v75, v75, v43
	v_mul_f32_e32 v76, v76, v44
	v_mul_f32_e32 v77, v77, v45
	v_mul_f32_e32 v78, v78, v46
	v_mul_f32_e32 v79, v79, v47
	s_waitcnt lgkmcnt(0)
	v_add_f32_e32 v29, v29, v30
	ds_bpermute_b32 v30, v25, v29
	v_add_f32_e32 v96, 1.0, v96
	v_add_f32_e32 v97, 1.0, v97
	v_add_f32_e32 v98, 1.0, v98
	v_add_f32_e32 v99, 1.0, v99
	v_add_f32_e32 v100, 1.0, v100
	v_add_f32_e32 v101, 1.0, v101
	v_add_f32_e32 v102, 1.0, v102
	v_add_f32_e32 v103, 1.0, v103
	s_waitcnt lgkmcnt(0)
	v_add_f32_e32 v29, v29, v30
	ds_bpermute_b32 v30, v26, v29
	v_add_f32_e32 v104, 1.0, v104
	v_add_f32_e32 v105, 1.0, v105
	v_add_f32_e32 v106, 1.0, v106
	v_add_f32_e32 v107, 1.0, v107
	v_add_f32_e32 v108, 1.0, v108
	v_add_f32_e32 v109, 1.0, v109
	v_add_f32_e32 v110, 1.0, v110
	v_add_f32_e32 v111, 1.0, v111
	s_waitcnt lgkmcnt(0)
	v_add_f32_e32 v29, v29, v30
	ds_bpermute_b32 v30, v27, v29
	v_mul_f32_e32 v64, v64, v96
	v_mul_f32_e32 v65, v65, v97
	v_mul_f32_e32 v66, v66, v98
	v_mul_f32_e32 v67, v67, v99
	v_mul_f32_e32 v68, v68, v100
	v_mul_f32_e32 v69, v69, v101
	v_mul_f32_e32 v70, v70, v102
	v_mul_f32_e32 v71, v71, v103
	s_waitcnt lgkmcnt(0)
	v_add_f32_e32 v29, v29, v30
	ds_bpermute_b32 v30, v28, v29
	v_mul_f32_e32 v72, v72, v104
	v_mul_f32_e32 v73, v73, v105
	v_mul_f32_e32 v74, v74, v106
	v_mul_f32_e32 v75, v75, v107
	v_mul_f32_e32 v76, v76, v108
	v_mul_f32_e32 v77, v77, v109
	v_mul_f32_e32 v78, v78, v110
	v_mul_f32_e32 v79, v79, v111
	s_waitcnt lgkmcnt(0)
	v_add_f32_e32 v29, v29, v30
	s_mov_b64 s[22:23], exec
	s_mov_b64 exec, s[0:1]
	global_store_dword v19, v29, s[10:11]
	s_mov_b64 exec, s[22:23]
	v_cvt_pk_bf16_f32 v10, v64, v65
	v_cvt_pk_bf16_f32 v11, v66, v67
	v_cvt_pk_bf16_f32 v12, v68, v69
	v_cvt_pk_bf16_f32 v13, v70, v71
	v_cvt_pk_bf16_f32 v14, v72, v73
	v_cvt_pk_bf16_f32 v15, v74, v75
	v_cvt_pk_bf16_f32 v16, v76, v77
	v_cvt_pk_bf16_f32 v17, v78, v79
	global_store_dwordx2 v112, v[10:11], s[8:9]
	global_store_dwordx2 v112, v[12:13], s[8:9] offset:512
	global_store_dwordx2 v112, v[14:15], s[8:9] offset:1024
	global_store_dwordx2 v112, v[16:17], s[8:9] offset:1536
	s_add_u32 s10, s10, 0x2000
	s_addc_u32 s11, s11, 0
	s_add_u32 s8, s8, 0x400000
	s_addc_u32 s9, s9, 0
	s_cmpk_eq_u32 s98, 5
	s_cbranch_scc1 norm_nonext_4
	s_add_u32 s14, s14, 0x800000
	s_addc_u32 s15, s15, 0
	s_add_u32 s26, s26, 0x6000
	s_addc_u32 s27, s27, 0
	global_load_dwordx4 v[64:67], v18, s[14:15] nt
	global_load_dwordx4 v[68:71], v18, s[14:15] offset:1024 nt
	global_load_dwordx4 v[72:75], v18, s[14:15] offset:2048 nt
	global_load_dwordx4 v[76:79], v18, s[14:15] offset:3072 nt
	global_load_dwordx4 v[96:99], v18, s[26:27]
	global_load_dwordx4 v[100:103], v18, s[26:27] offset:1024
	global_load_dwordx4 v[104:107], v18, s[26:27] offset:2048
	global_load_dwordx4 v[108:111], v18, s[26:27] offset:3072
	s_waitcnt vmcnt(13)
	s_branch norm_go_4
norm_nonext_4:
	s_waitcnt vmcnt(5)
norm_go_4:
	v_mul_f32_e32 v29, v49, v49
	v_mul_f32_e32 v30, v51, v51
	v_mul_f32_e32 v31, v53, v53
	v_mul_f32_e32 v113, v55, v55
	v_mul_f32_e32 v114, v57, v57
	v_mul_f32_e32 v115, v59, v59
	v_mul_f32_e32 v116, v61, v61
	v_mul_f32_e32 v117, v63, v63
	v_fmac_f32_e32 v29, v48, v48
	v_fmac_f32_e32 v30, v50, v50
	v_fmac_f32_e32 v31, v52, v52
	v_fmac_f32_e32 v113, v54, v54
	v_fmac_f32_e32 v114, v56, v56
	v_fmac_f32_e32 v115, v58, v58
	v_fmac_f32_e32 v116, v60, v60
	v_fmac_f32_e32 v117, v62, v62
	v_add_f32_e32 v29, v29, v30
	v_add_f32_e32 v31, v31, v113
	v_add_f32_e32 v114, v114, v115
	v_add_f32_e32 v116, v116, v117
	v_add_f32_e32 v29, v29, v31
	v_add_f32_e32 v29, v29, v114
	v_add_f32_e32 v29, v29, v116
	ds_bpermute_b32 v30, v1, v29
	v_mul_f32_e32 v48, v48, v32
	v_mul_f32_e32 v49, v49, v33
	v_mul_f32_e32 v50, v50, v34
	v_mul_f32_e32 v51, v51, v35
	v_mul_f32_e32 v52, v52, v36
	v_mul_f32_e32 v53, v53, v37
	v_mul_f32_e32 v54, v54, v38
	v_mul_f32_e32 v55, v55, v39
	s_waitcnt lgkmcnt(0)
	v_add_f32_e32 v29, v29, v30
	ds_bpermute_b32 v30, v24, v29
	v_mul_f32_e32 v56, v56, v40
	v_mul_f32_e32 v57, v57, v41
	v_mul_f32_e32 v58, v58, v42
	v_mul_f32_e32 v59, v59, v43
	v_mul_f32_e32 v60, v60, v44
	v_mul_f32_e32 v61, v61, v45
	v_mul_f32_e32 v62, v62, v46
	v_mul_f32_e32 v63, v63, v47
	s_waitcnt lgkmcnt(0)
	v_add_f32_e32 v29, v29, v30
	ds_bpermute_b32 v30, v25, v29
	v_add_f32_e32 v80, 1.0, v80
	v_add_f32_e32 v81, 1.0, v81
	v_add_f32_e32 v82, 1.0, v82
	v_add_f32_e32 v83, 1.0, v83
	v_add_f32_e32 v84, 1.0, v84
	v_add_f32_e32 v85, 1.0, v85
	v_add_f32_e32 v86, 1.0, v86
	v_add_f32_e32 v87, 1.0, v87
	s_waitcnt lgkmcnt(0)
	v_add_f32_e32 v29, v29, v30
	ds_bpermute_b32 v30, v26, v29
	v_add_f32_e32 v88, 1.0, v88
	v_add_f32_e32 v89, 1.0, v89
	v_add_f32_e32 v90, 1.0, v90
	v_add_f32_e32 v91, 1.0, v91
	v_add_f32_e32 v92, 1.0, v92
	v_add_f32_e32 v93, 1.0, v93
	v_add_f32_e32 v94, 1.0, v94
	v_add_f32_e32 v95, 1.0, v95
	s_waitcnt lgkmcnt(0)
	v_add_f32_e32 v29, v29, v30
	ds_bpermute_b32 v30, v27, v29
	v_mul_f32_e32 v48, v48, v80
	v_mul_f32_e32 v49, v49, v81
	v_mul_f32_e32 v50, v50, v82
	v_mul_f32_e32 v51, v51, v83
	v_mul_f32_e32 v52, v52, v84
	v_mul_f32_e32 v53, v53, v85
	v_mul_f32_e32 v54, v54, v86
	v_mul_f32_e32 v55, v55, v87
	s_waitcnt lgkmcnt(0)
	v_add_f32_e32 v29, v29, v30
	ds_bpermute_b32 v30, v28, v29
	v_mul_f32_e32 v56, v56, v88
	v_mul_f32_e32 v57, v57, v89
	v_mul_f32_e32 v58, v58, v90
	v_mul_f32_e32 v59, v59, v91
	v_mul_f32_e32 v60, v60, v92
	v_mul_f32_e32 v61, v61, v93
	v_mul_f32_e32 v62, v62, v94
	v_mul_f32_e32 v63, v63, v95
	s_waitcnt lgkmcnt(0)
	v_add_f32_e32 v29, v29, v30
	s_mov_b64 s[22:23], exec
	s_mov_b64 exec, s[0:1]
	global_store_dword v19, v29, s[10:11]
	s_mov_b64 exec, s[22:23]
	v_cvt_pk_bf16_f32 v2, v48, v49
	v_cvt_pk_bf16_f32 v3, v50, v51
	v_cvt_pk_bf16_f32 v4, v52, v53
	v_cvt_pk_bf16_f32 v5, v54, v55
	v_cvt_pk_bf16_f32 v6, v56, v57
	v_cvt_pk_bf16_f32 v7, v58, v59
	v_cvt_pk_bf16_f32 v8, v60, v61
	v_cvt_pk_bf16_f32 v9, v62, v63
	global_store_dwordx2 v112, v[2:3], s[8:9]
	global_store_dwordx2 v112, v[4:5], s[8:9] offset:512
	global_store_dwordx2 v112, v[6:7], s[8:9] offset:1024
	global_store_dwordx2 v112, v[8:9], s[8:9] offset:1536
	s_add_u32 s10, s10, 0x2000
	s_addc_u32 s11, s11, 0
	s_add_u32 s8, s8, 0x400000
	s_addc_u32 s9, s9, 0
	s_cmpk_eq_u32 s98, 5
	s_cbranch_scc1 .LBB0_117
	s_add_u32 s14, s14, 0x800000
	s_addc_u32 s15, s15, 0
	s_add_u32 s26, s26, 0x6000
	s_addc_u32 s27, s27, 0
	global_load_dwordx4 v[48:51], v18, s[14:15] nt
	global_load_dwordx4 v[52:55], v18, s[14:15] offset:1024 nt
	global_load_dwordx4 v[56:59], v18, s[14:15] offset:2048 nt
	global_load_dwordx4 v[60:63], v18, s[14:15] offset:3072 nt
	global_load_dwordx4 v[80:83], v18, s[26:27]
	global_load_dwordx4 v[84:87], v18, s[26:27] offset:1024
	global_load_dwordx4 v[88:91], v18, s[26:27] offset:2048
	global_load_dwordx4 v[92:95], v18, s[26:27] offset:3072
	s_waitcnt vmcnt(13)
	v_mul_f32_e32 v29, v65, v65
	v_mul_f32_e32 v30, v67, v67
	v_mul_f32_e32 v31, v69, v69
	v_mul_f32_e32 v113, v71, v71
	v_mul_f32_e32 v114, v73, v73
	v_mul_f32_e32 v115, v75, v75
	v_mul_f32_e32 v116, v77, v77
	v_mul_f32_e32 v117, v79, v79
	v_fmac_f32_e32 v29, v64, v64
	v_fmac_f32_e32 v30, v66, v66
	v_fmac_f32_e32 v31, v68, v68
	v_fmac_f32_e32 v113, v70, v70
	v_fmac_f32_e32 v114, v72, v72
	v_fmac_f32_e32 v115, v74, v74
	v_fmac_f32_e32 v116, v76, v76
	v_fmac_f32_e32 v117, v78, v78
	v_add_f32_e32 v29, v29, v30
	v_add_f32_e32 v31, v31, v113
	v_add_f32_e32 v114, v114, v115
	v_add_f32_e32 v116, v116, v117
	v_add_f32_e32 v29, v29, v31
	v_add_f32_e32 v29, v29, v114
	v_add_f32_e32 v29, v29, v116
	ds_bpermute_b32 v30, v1, v29
	v_mul_f32_e32 v64, v64, v32
	v_mul_f32_e32 v65, v65, v33
	v_mul_f32_e32 v66, v66, v34
	v_mul_f32_e32 v67, v67, v35
	v_mul_f32_e32 v68, v68, v36
	v_mul_f32_e32 v69, v69, v37
	v_mul_f32_e32 v70, v70, v38
	v_mul_f32_e32 v71, v71, v39
	s_waitcnt lgkmcnt(0)
	v_add_f32_e32 v29, v29, v30
	ds_bpermute_b32 v30, v24, v29
	v_mul_f32_e32 v72, v72, v40
	v_mul_f32_e32 v73, v73, v41
	v_mul_f32_e32 v74, v74, v42
	v_mul_f32_e32 v75, v75, v43
	v_mul_f32_e32 v76, v76, v44
	v_mul_f32_e32 v77, v77, v45
	v_mul_f32_e32 v78, v78, v46
	v_mul_f32_e32 v79, v79, v47
	s_waitcnt lgkmcnt(0)
	v_add_f32_e32 v29, v29, v30
	ds_bpermute_b32 v30, v25, v29
	v_add_f32_e32 v96, 1.0, v96
	v_add_f32_e32 v97, 1.0, v97
	v_add_f32_e32 v98, 1.0, v98
	v_add_f32_e32 v99, 1.0, v99
	v_add_f32_e32 v100, 1.0, v100
	v_add_f32_e32 v101, 1.0, v101
	v_add_f32_e32 v102, 1.0, v102
	v_add_f32_e32 v103, 1.0, v103
	s_waitcnt lgkmcnt(0)
	v_add_f32_e32 v29, v29, v30
	ds_bpermute_b32 v30, v26, v29
	v_add_f32_e32 v104, 1.0, v104
	v_add_f32_e32 v105, 1.0, v105
	v_add_f32_e32 v106, 1.0, v106
	v_add_f32_e32 v107, 1.0, v107
	v_add_f32_e32 v108, 1.0, v108
	v_add_f32_e32 v109, 1.0, v109
	v_add_f32_e32 v110, 1.0, v110
	v_add_f32_e32 v111, 1.0, v111
	s_waitcnt lgkmcnt(0)
	v_add_f32_e32 v29, v29, v30
	ds_bpermute_b32 v30, v27, v29
	v_mul_f32_e32 v64, v64, v96
	v_mul_f32_e32 v65, v65, v97
	v_mul_f32_e32 v66, v66, v98
	v_mul_f32_e32 v67, v67, v99
	v_mul_f32_e32 v68, v68, v100
	v_mul_f32_e32 v69, v69, v101
	v_mul_f32_e32 v70, v70, v102
	v_mul_f32_e32 v71, v71, v103
	s_waitcnt lgkmcnt(0)
	v_add_f32_e32 v29, v29, v30
	ds_bpermute_b32 v30, v28, v29
	v_mul_f32_e32 v72, v72, v104
	v_mul_f32_e32 v73, v73, v105
	v_mul_f32_e32 v74, v74, v106
	v_mul_f32_e32 v75, v75, v107
	v_mul_f32_e32 v76, v76, v108
	v_mul_f32_e32 v77, v77, v109
	v_mul_f32_e32 v78, v78, v110
	v_mul_f32_e32 v79, v79, v111
	s_waitcnt lgkmcnt(0)
	v_add_f32_e32 v29, v29, v30
	s_mov_b64 s[22:23], exec
	s_mov_b64 exec, s[0:1]
	global_store_dword v19, v29, s[10:11]
	s_mov_b64 exec, s[22:23]
	v_cvt_pk_bf16_f32 v10, v64, v65
	v_cvt_pk_bf16_f32 v11, v66, v67
	v_cvt_pk_bf16_f32 v12, v68, v69
	v_cvt_pk_bf16_f32 v13, v70, v71
	v_cvt_pk_bf16_f32 v14, v72, v73
	v_cvt_pk_bf16_f32 v15, v74, v75
	v_cvt_pk_bf16_f32 v16, v76, v77
	v_cvt_pk_bf16_f32 v17, v78, v79
	global_store_dwordx2 v112, v[10:11], s[8:9]
	global_store_dwordx2 v112, v[12:13], s[8:9] offset:512
	global_store_dwordx2 v112, v[14:15], s[8:9] offset:1024
	global_store_dwordx2 v112, v[16:17], s[8:9] offset:1536
	s_add_u32 s10, s10, 0x2000
	s_addc_u32 s11, s11, 0
	s_add_u32 s8, s8, 0x400000
	s_addc_u32 s9, s9, 0
	s_add_u32 s14, s14, 0x800000
	s_addc_u32 s15, s15, 0
	s_add_u32 s26, s26, 0x6000
	s_addc_u32 s27, s27, 0
	global_load_dwordx4 v[64:67], v18, s[14:15] nt
	global_load_dwordx4 v[68:71], v18, s[14:15] offset:1024 nt
	global_load_dwordx4 v[72:75], v18, s[14:15] offset:2048 nt
	global_load_dwordx4 v[76:79], v18, s[14:15] offset:3072 nt
	global_load_dwordx4 v[96:99], v18, s[26:27]
	global_load_dwordx4 v[100:103], v18, s[26:27] offset:1024
	global_load_dwordx4 v[104:107], v18, s[26:27] offset:2048
	global_load_dwordx4 v[108:111], v18, s[26:27] offset:3072
	s_waitcnt vmcnt(13)
	v_mul_f32_e32 v29, v49, v49
	v_mul_f32_e32 v30, v51, v51
	v_mul_f32_e32 v31, v53, v53
	v_mul_f32_e32 v113, v55, v55
	v_mul_f32_e32 v114, v57, v57
	v_mul_f32_e32 v115, v59, v59
	v_mul_f32_e32 v116, v61, v61
	v_mul_f32_e32 v117, v63, v63
	v_fmac_f32_e32 v29, v48, v48
	v_fmac_f32_e32 v30, v50, v50
	v_fmac_f32_e32 v31, v52, v52
	v_fmac_f32_e32 v113, v54, v54
	v_fmac_f32_e32 v114, v56, v56
	v_fmac_f32_e32 v115, v58, v58
	v_fmac_f32_e32 v116, v60, v60
	v_fmac_f32_e32 v117, v62, v62
	v_add_f32_e32 v29, v29, v30
	v_add_f32_e32 v31, v31, v113
	v_add_f32_e32 v114, v114, v115
	v_add_f32_e32 v116, v116, v117
	v_add_f32_e32 v29, v29, v31
	v_add_f32_e32 v29, v29, v114
	v_add_f32_e32 v29, v29, v116
	ds_bpermute_b32 v30, v1, v29
	v_mul_f32_e32 v48, v48, v32
	v_mul_f32_e32 v49, v49, v33
	v_mul_f32_e32 v50, v50, v34
	v_mul_f32_e32 v51, v51, v35
	v_mul_f32_e32 v52, v52, v36
	v_mul_f32_e32 v53, v53, v37
	v_mul_f32_e32 v54, v54, v38
	v_mul_f32_e32 v55, v55, v39
	s_waitcnt lgkmcnt(0)
	v_add_f32_e32 v29, v29, v30
	ds_bpermute_b32 v30, v24, v29
	v_mul_f32_e32 v56, v56, v40
	v_mul_f32_e32 v57, v57, v41
	v_mul_f32_e32 v58, v58, v42
	v_mul_f32_e32 v59, v59, v43
	v_mul_f32_e32 v60, v60, v44
	v_mul_f32_e32 v61, v61, v45
	v_mul_f32_e32 v62, v62, v46
	v_mul_f32_e32 v63, v63, v47
	s_waitcnt lgkmcnt(0)
	v_add_f32_e32 v29, v29, v30
	ds_bpermute_b32 v30, v25, v29
	v_add_f32_e32 v80, 1.0, v80
	v_add_f32_e32 v81, 1.0, v81
	v_add_f32_e32 v82, 1.0, v82
	v_add_f32_e32 v83, 1.0, v83
	v_add_f32_e32 v84, 1.0, v84
	v_add_f32_e32 v85, 1.0, v85
	v_add_f32_e32 v86, 1.0, v86
	v_add_f32_e32 v87, 1.0, v87
	s_waitcnt lgkmcnt(0)
	v_add_f32_e32 v29, v29, v30
	ds_bpermute_b32 v30, v26, v29
	v_add_f32_e32 v88, 1.0, v88
	v_add_f32_e32 v89, 1.0, v89
	v_add_f32_e32 v90, 1.0, v90
	v_add_f32_e32 v91, 1.0, v91
	v_add_f32_e32 v92, 1.0, v92
	v_add_f32_e32 v93, 1.0, v93
	v_add_f32_e32 v94, 1.0, v94
	v_add_f32_e32 v95, 1.0, v95
	s_waitcnt lgkmcnt(0)
	v_add_f32_e32 v29, v29, v30
	ds_bpermute_b32 v30, v27, v29
	v_mul_f32_e32 v48, v48, v80
	v_mul_f32_e32 v49, v49, v81
	v_mul_f32_e32 v50, v50, v82
	v_mul_f32_e32 v51, v51, v83
	v_mul_f32_e32 v52, v52, v84
	v_mul_f32_e32 v53, v53, v85
	v_mul_f32_e32 v54, v54, v86
	v_mul_f32_e32 v55, v55, v87
	s_waitcnt lgkmcnt(0)
	v_add_f32_e32 v29, v29, v30
	ds_bpermute_b32 v30, v28, v29
	v_mul_f32_e32 v56, v56, v88
	v_mul_f32_e32 v57, v57, v89
	v_mul_f32_e32 v58, v58, v90
	v_mul_f32_e32 v59, v59, v91
	v_mul_f32_e32 v60, v60, v92
	v_mul_f32_e32 v61, v61, v93
	v_mul_f32_e32 v62, v62, v94
	v_mul_f32_e32 v63, v63, v95
	s_waitcnt lgkmcnt(0)
	v_add_f32_e32 v29, v29, v30
	s_mov_b64 s[22:23], exec
	s_mov_b64 exec, s[0:1]
	global_store_dword v19, v29, s[10:11]
	s_mov_b64 exec, s[22:23]
	v_cvt_pk_bf16_f32 v2, v48, v49
	v_cvt_pk_bf16_f32 v3, v50, v51
	v_cvt_pk_bf16_f32 v4, v52, v53
	v_cvt_pk_bf16_f32 v5, v54, v55
	v_cvt_pk_bf16_f32 v6, v56, v57
	v_cvt_pk_bf16_f32 v7, v58, v59
	v_cvt_pk_bf16_f32 v8, v60, v61
	v_cvt_pk_bf16_f32 v9, v62, v63
	global_store_dwordx2 v112, v[2:3], s[8:9]
	global_store_dwordx2 v112, v[4:5], s[8:9] offset:512
	global_store_dwordx2 v112, v[6:7], s[8:9] offset:1024
	global_store_dwordx2 v112, v[8:9], s[8:9] offset:1536
	s_add_u32 s10, s10, 0x2000
	s_addc_u32 s11, s11, 0
	s_add_u32 s8, s8, 0x400000
	s_addc_u32 s9, s9, 0
	s_add_u32 s26, s26, 0x6000
	s_addc_u32 s27, s27, 0
	global_load_dwordx4 v[48:51], v18, s[36:37] nt
	global_load_dwordx4 v[52:55], v18, s[36:37] offset:1024 nt
	global_load_dwordx4 v[56:59], v18, s[36:37] offset:2048 nt
	global_load_dwordx4 v[60:63], v18, s[36:37] offset:3072 nt
	global_load_dwordx4 v[80:83], v18, s[26:27]
	global_load_dwordx4 v[84:87], v18, s[26:27] offset:1024
	global_load_dwordx4 v[88:91], v18, s[26:27] offset:2048
	global_load_dwordx4 v[92:95], v18, s[26:27] offset:3072
	s_waitcnt vmcnt(13)
	v_mul_f32_e32 v29, v65, v65
	v_mul_f32_e32 v30, v67, v67
	v_mul_f32_e32 v31, v69, v69
	v_mul_f32_e32 v113, v71, v71
	v_mul_f32_e32 v114, v73, v73
	v_mul_f32_e32 v115, v75, v75
	v_mul_f32_e32 v116, v77, v77
	v_mul_f32_e32 v117, v79, v79
	v_fmac_f32_e32 v29, v64, v64
	v_fmac_f32_e32 v30, v66, v66
	v_fmac_f32_e32 v31, v68, v68
	v_fmac_f32_e32 v113, v70, v70
	v_fmac_f32_e32 v114, v72, v72
	v_fmac_f32_e32 v115, v74, v74
	v_fmac_f32_e32 v116, v76, v76
	v_fmac_f32_e32 v117, v78, v78
	v_add_f32_e32 v29, v29, v30
	v_add_f32_e32 v31, v31, v113
	v_add_f32_e32 v114, v114, v115
	v_add_f32_e32 v116, v116, v117
	v_add_f32_e32 v29, v29, v31
	v_add_f32_e32 v29, v29, v114
	v_add_f32_e32 v29, v29, v116
	ds_bpermute_b32 v30, v1, v29
	v_mul_f32_e32 v64, v64, v32
	v_mul_f32_e32 v65, v65, v33
	v_mul_f32_e32 v66, v66, v34
	v_mul_f32_e32 v67, v67, v35
	v_mul_f32_e32 v68, v68, v36
	v_mul_f32_e32 v69, v69, v37
	v_mul_f32_e32 v70, v70, v38
	v_mul_f32_e32 v71, v71, v39
	s_waitcnt lgkmcnt(0)
	v_add_f32_e32 v29, v29, v30
	ds_bpermute_b32 v30, v24, v29
	v_mul_f32_e32 v72, v72, v40
	v_mul_f32_e32 v73, v73, v41
	v_mul_f32_e32 v74, v74, v42
	v_mul_f32_e32 v75, v75, v43
	v_mul_f32_e32 v76, v76, v44
	v_mul_f32_e32 v77, v77, v45
	v_mul_f32_e32 v78, v78, v46
	v_mul_f32_e32 v79, v79, v47
	s_waitcnt lgkmcnt(0)
	v_add_f32_e32 v29, v29, v30
	ds_bpermute_b32 v30, v25, v29
	v_add_f32_e32 v96, 1.0, v96
	v_add_f32_e32 v97, 1.0, v97
	v_add_f32_e32 v98, 1.0, v98
	v_add_f32_e32 v99, 1.0, v99
	v_add_f32_e32 v100, 1.0, v100
	v_add_f32_e32 v101, 1.0, v101
	v_add_f32_e32 v102, 1.0, v102
	v_add_f32_e32 v103, 1.0, v103
	s_waitcnt lgkmcnt(0)
	v_add_f32_e32 v29, v29, v30
	ds_bpermute_b32 v30, v26, v29
	v_add_f32_e32 v104, 1.0, v104
	v_add_f32_e32 v105, 1.0, v105
	v_add_f32_e32 v106, 1.0, v106
	v_add_f32_e32 v107, 1.0, v107
	v_add_f32_e32 v108, 1.0, v108
	v_add_f32_e32 v109, 1.0, v109
	v_add_f32_e32 v110, 1.0, v110
	v_add_f32_e32 v111, 1.0, v111
	s_waitcnt lgkmcnt(0)
	v_add_f32_e32 v29, v29, v30
	ds_bpermute_b32 v30, v27, v29
	v_mul_f32_e32 v64, v64, v96
	v_mul_f32_e32 v65, v65, v97
	v_mul_f32_e32 v66, v66, v98
	v_mul_f32_e32 v67, v67, v99
	v_mul_f32_e32 v68, v68, v100
	v_mul_f32_e32 v69, v69, v101
	v_mul_f32_e32 v70, v70, v102
	v_mul_f32_e32 v71, v71, v103
	s_waitcnt lgkmcnt(0)
	v_add_f32_e32 v29, v29, v30
	ds_bpermute_b32 v30, v28, v29
	v_mul_f32_e32 v72, v72, v104
	v_mul_f32_e32 v73, v73, v105
	v_mul_f32_e32 v74, v74, v106
	v_mul_f32_e32 v75, v75, v107
	v_mul_f32_e32 v76, v76, v108
	v_mul_f32_e32 v77, v77, v109
	v_mul_f32_e32 v78, v78, v110
	v_mul_f32_e32 v79, v79, v111
	s_waitcnt lgkmcnt(0)
	v_add_f32_e32 v29, v29, v30
	s_mov_b64 s[22:23], exec
	s_mov_b64 exec, s[0:1]
	global_store_dword v19, v29, s[10:11]
	s_mov_b64 exec, s[22:23]
	v_cvt_pk_bf16_f32 v10, v64, v65
	v_cvt_pk_bf16_f32 v11, v66, v67
	v_cvt_pk_bf16_f32 v12, v68, v69
	v_cvt_pk_bf16_f32 v13, v70, v71
	v_cvt_pk_bf16_f32 v14, v72, v73
	v_cvt_pk_bf16_f32 v15, v74, v75
	v_cvt_pk_bf16_f32 v16, v76, v77
	v_cvt_pk_bf16_f32 v17, v78, v79
	global_store_dwordx2 v112, v[10:11], s[8:9]
	global_store_dwordx2 v112, v[12:13], s[8:9] offset:512
	global_store_dwordx2 v112, v[14:15], s[8:9] offset:1024
	global_store_dwordx2 v112, v[16:17], s[8:9] offset:1536
	s_add_u32 s10, s10, 0x2000
	s_addc_u32 s11, s11, 0
	s_add_u32 s8, s8, 0x400000
	s_addc_u32 s9, s9, 0
	s_cmpk_lg_u32 s98, 10
	s_cbranch_scc1 norm_nonext_8
	s_lshl_b32 s12, s100, 11
	s_add_u32 s12, s12, s99
	s_cmpk_eq_u32 s100, 8
	s_cselect_b32 s14, s20, s16
	s_cselect_b32 s15, s21, s17
	s_cselect_b32 s13, s99, s12
	s_lshl_b32 s13, s13, 12
	s_add_u32 s14, s14, s13
	s_addc_u32 s15, s15, 0
	s_mul_i32 s13, s100, 0x6000
	s_add_u32 s26, s34, s13
	s_addc_u32 s27, s35, 0
	s_add_u32 s26, s26, 0x11000
	s_addc_u32 s27, s27, 0
	global_load_dwordx4 v[64:67], v18, s[14:15] nt
	global_load_dwordx4 v[68:71], v18, s[14:15] offset:1024 nt
	global_load_dwordx4 v[72:75], v18, s[14:15] offset:2048 nt
	global_load_dwordx4 v[76:79], v18, s[14:15] offset:3072 nt
	global_load_dwordx4 v[96:99], v18, s[26:27]
	global_load_dwordx4 v[100:103], v18, s[26:27] offset:1024
	global_load_dwordx4 v[104:107], v18, s[26:27] offset:2048
	global_load_dwordx4 v[108:111], v18, s[26:27] offset:3072
	s_waitcnt vmcnt(13)
	s_branch norm_go_8
norm_nonext_8:
	s_waitcnt vmcnt(5)
norm_go_8:
	v_mul_f32_e32 v29, v49, v49
	v_mul_f32_e32 v30, v51, v51
	v_mul_f32_e32 v31, v53, v53
	v_mul_f32_e32 v113, v55, v55
	v_mul_f32_e32 v114, v57, v57
	v_mul_f32_e32 v115, v59, v59
	v_mul_f32_e32 v116, v61, v61
	v_mul_f32_e32 v117, v63, v63
	v_fmac_f32_e32 v29, v48, v48
	v_fmac_f32_e32 v30, v50, v50
	v_fmac_f32_e32 v31, v52, v52
	v_fmac_f32_e32 v113, v54, v54
	v_fmac_f32_e32 v114, v56, v56
	v_fmac_f32_e32 v115, v58, v58
	v_fmac_f32_e32 v116, v60, v60
	v_fmac_f32_e32 v117, v62, v62
	v_add_f32_e32 v29, v29, v30
	v_add_f32_e32 v31, v31, v113
	v_add_f32_e32 v114, v114, v115
	v_add_f32_e32 v116, v116, v117
	v_add_f32_e32 v29, v29, v31
	v_add_f32_e32 v29, v29, v114
	v_add_f32_e32 v29, v29, v116
	ds_bpermute_b32 v30, v1, v29
	v_mul_f32_e32 v48, v48, v32
	v_mul_f32_e32 v49, v49, v33
	v_mul_f32_e32 v50, v50, v34
	v_mul_f32_e32 v51, v51, v35
	v_mul_f32_e32 v52, v52, v36
	v_mul_f32_e32 v53, v53, v37
	v_mul_f32_e32 v54, v54, v38
	v_mul_f32_e32 v55, v55, v39
	s_waitcnt lgkmcnt(0)
	v_add_f32_e32 v29, v29, v30
	ds_bpermute_b32 v30, v24, v29
	v_mul_f32_e32 v56, v56, v40
	v_mul_f32_e32 v57, v57, v41
	v_mul_f32_e32 v58, v58, v42
	v_mul_f32_e32 v59, v59, v43
	v_mul_f32_e32 v60, v60, v44
	v_mul_f32_e32 v61, v61, v45
	v_mul_f32_e32 v62, v62, v46
	v_mul_f32_e32 v63, v63, v47
	s_waitcnt lgkmcnt(0)
	v_add_f32_e32 v29, v29, v30
	ds_bpermute_b32 v30, v25, v29
	v_add_f32_e32 v80, 1.0, v80
	v_add_f32_e32 v81, 1.0, v81
	v_add_f32_e32 v82, 1.0, v82
	v_add_f32_e32 v83, 1.0, v83
	v_add_f32_e32 v84, 1.0, v84
	v_add_f32_e32 v85, 1.0, v85
	v_add_f32_e32 v86, 1.0, v86
	v_add_f32_e32 v87, 1.0, v87
	s_waitcnt lgkmcnt(0)
	v_add_f32_e32 v29, v29, v30
	ds_bpermute_b32 v30, v26, v29
	v_add_f32_e32 v88, 1.0, v88
	v_add_f32_e32 v89, 1.0, v89
	v_add_f32_e32 v90, 1.0, v90
	v_add_f32_e32 v91, 1.0, v91
	v_add_f32_e32 v92, 1.0, v92
	v_add_f32_e32 v93, 1.0, v93
	v_add_f32_e32 v94, 1.0, v94
	v_add_f32_e32 v95, 1.0, v95
	s_waitcnt lgkmcnt(0)
	v_add_f32_e32 v29, v29, v30
	ds_bpermute_b32 v30, v27, v29
	v_mul_f32_e32 v48, v48, v80
	v_mul_f32_e32 v49, v49, v81
	v_mul_f32_e32 v50, v50, v82
	v_mul_f32_e32 v51, v51, v83
	v_mul_f32_e32 v52, v52, v84
	v_mul_f32_e32 v53, v53, v85
	v_mul_f32_e32 v54, v54, v86
	v_mul_f32_e32 v55, v55, v87
	s_waitcnt lgkmcnt(0)
	v_add_f32_e32 v29, v29, v30
	ds_bpermute_b32 v30, v28, v29
	v_mul_f32_e32 v56, v56, v88
	v_mul_f32_e32 v57, v57, v89
	v_mul_f32_e32 v58, v58, v90
	v_mul_f32_e32 v59, v59, v91
	v_mul_f32_e32 v60, v60, v92
	v_mul_f32_e32 v61, v61, v93
	v_mul_f32_e32 v62, v62, v94
	v_mul_f32_e32 v63, v63, v95
	s_waitcnt lgkmcnt(0)
	v_add_f32_e32 v29, v29, v30
	s_mov_b64 s[22:23], exec
	s_mov_b64 exec, s[0:1]
	global_store_dword v19, v29, s[10:11]
	s_mov_b64 exec, s[22:23]
	v_cvt_pk_bf16_f32 v2, v48, v49
	v_cvt_pk_bf16_f32 v3, v50, v51
	v_cvt_pk_bf16_f32 v4, v52, v53
	v_cvt_pk_bf16_f32 v5, v54, v55
	v_cvt_pk_bf16_f32 v6, v56, v57
	v_cvt_pk_bf16_f32 v7, v58, v59
	v_cvt_pk_bf16_f32 v8, v60, v61
	v_cvt_pk_bf16_f32 v9, v62, v63
	global_store_dwordx2 v112, v[2:3], s[8:9]
	global_store_dwordx2 v112, v[4:5], s[8:9] offset:512
	global_store_dwordx2 v112, v[6:7], s[8:9] offset:1024
	global_store_dwordx2 v112, v[8:9], s[8:9] offset:1536
	s_cmpk_lg_u32 s98, 10
	s_cbranch_scc1 .LBB0_117
	s_waitcnt vmcnt(5)
	s_lshl_b32 s13, s12, 11
	s_add_u32 s8, s34, s13
	s_addc_u32 s9, s35, 0
	s_add_u32 s8, s8, 0x3500000
	s_addc_u32 s9, s9, 0
	s_lshl_b32 s13, s12, 2
	s_add_u32 s10, s34, s13
	s_addc_u32 s11, s35, 0
	s_add_u32 s10, s10, 0xb6000
	s_addc_u32 s11, s11, 0
	v_mul_f32_e32 v29, v65, v65
	v_mul_f32_e32 v30, v67, v67
	v_mul_f32_e32 v31, v69, v69
	v_mul_f32_e32 v113, v71, v71
	v_mul_f32_e32 v114, v73, v73
	v_mul_f32_e32 v115, v75, v75
	v_mul_f32_e32 v116, v77, v77
	v_mul_f32_e32 v117, v79, v79
	v_fmac_f32_e32 v29, v64, v64
	v_fmac_f32_e32 v30, v66, v66
	v_fmac_f32_e32 v31, v68, v68
	v_fmac_f32_e32 v113, v70, v70
	v_fmac_f32_e32 v114, v72, v72
	v_fmac_f32_e32 v115, v74, v74
	v_fmac_f32_e32 v116, v76, v76
	v_fmac_f32_e32 v117, v78, v78
	v_add_f32_e32 v29, v29, v30
	v_add_f32_e32 v31, v31, v113
	v_add_f32_e32 v114, v114, v115
	v_add_f32_e32 v116, v116, v117
	v_add_f32_e32 v29, v29, v31
	v_add_f32_e32 v29, v29, v114
	v_add_f32_e32 v29, v29, v116
	ds_bpermute_b32 v30, v1, v29
	v_mul_f32_e32 v64, v64, v32
	v_mul_f32_e32 v65, v65, v33
	v_mul_f32_e32 v66, v66, v34
	v_mul_f32_e32 v67, v67, v35
	v_mul_f32_e32 v68, v68, v36
	v_mul_f32_e32 v69, v69, v37
	v_mul_f32_e32 v70, v70, v38
	v_mul_f32_e32 v71, v71, v39
	s_waitcnt lgkmcnt(0)
	v_add_f32_e32 v29, v29, v30
	ds_bpermute_b32 v30, v24, v29
	v_mul_f32_e32 v72, v72, v40
	v_mul_f32_e32 v73, v73, v41
	v_mul_f32_e32 v74, v74, v42
	v_mul_f32_e32 v75, v75, v43
	v_mul_f32_e32 v76, v76, v44
	v_mul_f32_e32 v77, v77, v45
	v_mul_f32_e32 v78, v78, v46
	v_mul_f32_e32 v79, v79, v47
	s_waitcnt lgkmcnt(0)
	v_add_f32_e32 v29, v29, v30
	ds_bpermute_b32 v30, v25, v29
	v_add_f32_e32 v96, 1.0, v96
	v_add_f32_e32 v97, 1.0, v97
	v_add_f32_e32 v98, 1.0, v98
	v_add_f32_e32 v99, 1.0, v99
	v_add_f32_e32 v100, 1.0, v100
	v_add_f32_e32 v101, 1.0, v101
	v_add_f32_e32 v102, 1.0, v102
	v_add_f32_e32 v103, 1.0, v103
	s_waitcnt lgkmcnt(0)
	v_add_f32_e32 v29, v29, v30
	ds_bpermute_b32 v30, v26, v29
	v_add_f32_e32 v104, 1.0, v104
	v_add_f32_e32 v105, 1.0, v105
	v_add_f32_e32 v106, 1.0, v106
	v_add_f32_e32 v107, 1.0, v107
	v_add_f32_e32 v108, 1.0, v108
	v_add_f32_e32 v109, 1.0, v109
	v_add_f32_e32 v110, 1.0, v110
	v_add_f32_e32 v111, 1.0, v111
	s_waitcnt lgkmcnt(0)
	v_add_f32_e32 v29, v29, v30
	ds_bpermute_b32 v30, v27, v29
	v_mul_f32_e32 v64, v64, v96
	v_mul_f32_e32 v65, v65, v97
	v_mul_f32_e32 v66, v66, v98
	v_mul_f32_e32 v67, v67, v99
	v_mul_f32_e32 v68, v68, v100
	v_mul_f32_e32 v69, v69, v101
	v_mul_f32_e32 v70, v70, v102
	v_mul_f32_e32 v71, v71, v103
	s_waitcnt lgkmcnt(0)
	v_add_f32_e32 v29, v29, v30
	ds_bpermute_b32 v30, v28, v29
	v_mul_f32_e32 v72, v72, v104
	v_mul_f32_e32 v73, v73, v105
	v_mul_f32_e32 v74, v74, v106
	v_mul_f32_e32 v75, v75, v107
	v_mul_f32_e32 v76, v76, v108
	v_mul_f32_e32 v77, v77, v109
	v_mul_f32_e32 v78, v78, v110
	v_mul_f32_e32 v79, v79, v111
	s_waitcnt lgkmcnt(0)
	v_add_f32_e32 v29, v29, v30
	s_mov_b64 s[22:23], exec
	s_mov_b64 exec, s[0:1]
	global_store_dword v19, v29, s[10:11]
	s_mov_b64 exec, s[22:23]
	v_cvt_pk_bf16_f32 v10, v64, v65
	v_cvt_pk_bf16_f32 v11, v66, v67
	v_cvt_pk_bf16_f32 v12, v68, v69
	v_cvt_pk_bf16_f32 v13, v70, v71
	v_cvt_pk_bf16_f32 v14, v72, v73
	v_cvt_pk_bf16_f32 v15, v74, v75
	v_cvt_pk_bf16_f32 v16, v76, v77
	v_cvt_pk_bf16_f32 v17, v78, v79
	global_store_dwordx2 v112, v[10:11], s[8:9]
	global_store_dwordx2 v112, v[12:13], s[8:9] offset:512
	global_store_dwordx2 v112, v[14:15], s[8:9] offset:1024
	global_store_dwordx2 v112, v[16:17], s[8:9] offset:1536
	s_branch .LBB0_117

.LBB0_117:
	s_cmpk_ge_u32 s90, 0xc0
	s_cbranch_scc1 .LBB0_130
	s_mov_b64 s[0:1], s[34:35]
	v_mov_b32_e32 v1, v0
	s_mov_b32 s6, 0x38e38e39
	v_lshlrev_b32_e32 v2, 2, v1
	v_ashrrev_i32_e32 v69, 8, v1
	v_and_b32_e32 v73, 0x3fc, v2
	v_mul_hi_i32 v2, v69, s6
	v_lshrrev_b32_e32 v3, 31, v2
	v_ashrrev_i32_e32 v2, 1, v2
	v_add_u32_e32 v53, v2, v3
	s_add_u32 s8, s0, 0x10000
	v_lshl_add_u32 v2, v53, 3, v53
	s_addc_u32 s9, s1, 0
	v_sub_u32_e32 v52, v69, v2
	v_ashrrev_i32_e32 v2, 1, v53
	s_movk_i32 s5, 0x1800
	v_lshl_add_u32 v2, v2, 3, v2
	s_movk_i32 s1, 0x6000
	v_mov_b64_e32 v[50:51], s[8:9]
	v_mul_lo_u32 v4, v52, s5
	v_mad_i64_i32 v[2:3], s[8:9], v2, s1, v[50:51]
	v_ashrrev_i32_e32 v5, 31, v4
	v_lshl_add_u64 v[2:3], v[4:5], 2, v[2:3]
	v_bfe_i32 v4, v53, 0, 1
	v_and_b32_e32 v66, 0x3000, v4
	v_add_u32_e32 v4, 0x200, v1
	v_ashrrev_i32_e32 v71, 8, v4
	v_mul_hi_i32 v4, v71, s6
	v_lshrrev_b32_e32 v5, 31, v4
	v_ashrrev_i32_e32 v4, 1, v4
	v_add_u32_e32 v75, v4, v5
	v_lshl_add_u32 v4, v75, 3, v75
	v_sub_u32_e32 v68, v71, v4
	v_ashrrev_i32_e32 v4, 1, v75
	v_lshl_add_u32 v4, v4, 3, v4
	v_mul_lo_u32 v6, v68, s5
	v_mad_i64_i32 v[4:5], s[8:9], v4, s1, v[50:51]
	v_ashrrev_i32_e32 v7, 31, v6
	v_mov_b32_e32 v67, 0
	v_lshl_add_u64 v[4:5], v[6:7], 2, v[4:5]
	v_bfe_i32 v6, v75, 0, 1
	v_lshl_add_u64 v[2:3], v[2:3], 0, v[66:67]
	v_lshlrev_b32_e32 v66, 2, v73
	v_and_b32_e32 v6, 0x3000, v6
	v_mov_b32_e32 v7, v67
	v_lshl_add_u64 v[2:3], v[2:3], 0, v[66:67]
	v_lshl_add_u64 v[4:5], v[4:5], 0, v[6:7]
	v_lshl_add_u64 v[4:5], v[4:5], 0, v[66:67]
	global_load_dwordx4 v[38:41], v[2:3], off
	global_load_dwordx4 v[10:13], v[4:5], off
	v_add_u32_e32 v2, 0x400, v1
	v_ashrrev_i32_e32 v2, 8, v2
	v_mul_hi_i32 v3, v2, s6
	v_lshrrev_b32_e32 v4, 31, v3
	v_ashrrev_i32_e32 v3, 1, v3
	v_add_u32_e32 v77, v3, v4
	v_lshl_add_u32 v3, v77, 3, v77
	v_sub_u32_e32 v70, v2, v3
	v_ashrrev_i32_e32 v2, 1, v77
	v_lshl_add_u32 v2, v2, 3, v2
	v_mul_lo_u32 v4, v70, s5
	v_mad_i64_i32 v[2:3], s[8:9], v2, s1, v[50:51]
	v_ashrrev_i32_e32 v5, 31, v4
	v_lshl_add_u64 v[2:3], v[4:5], 2, v[2:3]
	v_bfe_i32 v4, v77, 0, 1
	v_and_b32_e32 v4, 0x3000, v4
	v_mov_b32_e32 v5, v67
	v_lshl_add_u64 v[2:3], v[2:3], 0, v[4:5]
	v_add_u32_e32 v4, 0x600, v1
	v_ashrrev_i32_e32 v4, 8, v4
	v_mul_hi_i32 v5, v4, s6
	v_lshrrev_b32_e32 v6, 31, v5
	v_ashrrev_i32_e32 v5, 1, v5
	v_add_u32_e32 v79, v5, v6
	v_lshl_add_u32 v5, v79, 3, v79
	v_sub_u32_e32 v72, v4, v5
	v_ashrrev_i32_e32 v4, 1, v79
	v_lshl_add_u32 v4, v4, 3, v4
	v_mul_lo_u32 v6, v72, s5
	v_mad_i64_i32 v[4:5], s[10:11], v4, s1, v[50:51]
	v_ashrrev_i32_e32 v7, 31, v6
	v_lshl_add_u64 v[4:5], v[6:7], 2, v[4:5]
	v_bfe_i32 v6, v79, 0, 1
	v_and_b32_e32 v6, 0x3000, v6
	v_mov_b32_e32 v7, v67
	v_lshl_add_u64 v[4:5], v[4:5], 0, v[6:7]
	v_add_u32_e32 v6, 0x800, v1
	v_ashrrev_i32_e32 v6, 8, v6
	v_mul_hi_i32 v7, v6, s6
	v_lshrrev_b32_e32 v8, 31, v7
	v_ashrrev_i32_e32 v7, 1, v7
	v_add_u32_e32 v81, v7, v8
	v_lshl_add_u32 v7, v81, 3, v81
	v_sub_u32_e32 v74, v6, v7
	v_ashrrev_i32_e32 v6, 1, v81
	v_lshl_add_u32 v6, v6, 3, v6
	v_mul_lo_u32 v8, v74, s5
	v_mad_i64_i32 v[6:7], s[10:11], v6, s1, v[50:51]
	v_ashrrev_i32_e32 v9, 31, v8
	v_lshl_add_u64 v[6:7], v[8:9], 2, v[6:7]
	v_bfe_i32 v8, v81, 0, 1
	v_and_b32_e32 v8, 0x3000, v8
	v_mov_b32_e32 v9, v67
	v_lshl_add_u64 v[6:7], v[6:7], 0, v[8:9]
	v_add_u32_e32 v8, 0xa00, v1
	v_ashrrev_i32_e32 v8, 8, v8
	v_mul_hi_i32 v9, v8, s6
	v_lshrrev_b32_e32 v18, 31, v9
	v_ashrrev_i32_e32 v9, 1, v9
	v_add_u32_e32 v83, v9, v18
	v_lshl_add_u32 v9, v83, 3, v83
	v_sub_u32_e32 v76, v8, v9
	v_ashrrev_i32_e32 v8, 1, v83
	v_lshl_add_u32 v8, v8, 3, v8
	v_mul_lo_u32 v18, v76, s5
	v_mad_i64_i32 v[8:9], s[10:11], v8, s1, v[50:51]
	v_ashrrev_i32_e32 v19, 31, v18
	v_lshl_add_u64 v[8:9], v[18:19], 2, v[8:9]
	v_bfe_i32 v18, v83, 0, 1
	v_lshl_add_u64 v[2:3], v[2:3], 0, v[66:67]
	v_lshl_add_u64 v[4:5], v[4:5], 0, v[66:67]
	v_and_b32_e32 v18, 0x3000, v18
	v_mov_b32_e32 v19, v67
	global_load_dwordx4 v[14:17], v[2:3], off
	s_nop 0
	global_load_dwordx4 v[2:5], v[4:5], off
	v_lshl_add_u64 v[8:9], v[8:9], 0, v[18:19]
	v_add_u32_e32 v18, 0xc00, v1
	v_ashrrev_i32_e32 v18, 8, v18
	v_mul_hi_i32 v19, v18, s6
	v_add_u32_e32 v54, 0x1800, v1
	v_lshrrev_b32_e32 v20, 31, v19
	v_ashrrev_i32_e32 v19, 1, v19
	v_ashrrev_i32_e32 v54, 8, v54
	v_add_u32_e32 v85, v19, v20
	v_mul_hi_i32 v55, v54, s6
	v_lshl_add_u32 v19, v85, 3, v85
	v_lshrrev_b32_e32 v56, 31, v55
	v_ashrrev_i32_e32 v55, 1, v55
	v_sub_u32_e32 v78, v18, v19
	v_ashrrev_i32_e32 v18, 1, v85
	v_add_u32_e32 v97, v55, v56
	v_lshl_add_u32 v18, v18, 3, v18
	v_mul_lo_u32 v20, v78, s5
	v_lshl_add_u32 v55, v97, 3, v97
	v_mad_i64_i32 v[18:19], s[10:11], v18, s1, v[50:51]
	v_ashrrev_i32_e32 v21, 31, v20
	v_sub_u32_e32 v90, v54, v55
	v_ashrrev_i32_e32 v54, 1, v97
	v_lshl_add_u64 v[18:19], v[20:21], 2, v[18:19]
	v_bfe_i32 v20, v85, 0, 1
	v_lshl_add_u32 v54, v54, 3, v54
	v_mul_lo_u32 v56, v90, s5
	v_and_b32_e32 v20, 0x3000, v20
	v_mov_b32_e32 v21, v67
	v_mad_i64_i32 v[54:55], s[10:11], v54, s1, v[50:51]
	v_ashrrev_i32_e32 v57, 31, v56
	v_lshl_add_u64 v[18:19], v[18:19], 0, v[20:21]
	v_add_u32_e32 v20, 0xe00, v1
	v_lshl_add_u64 v[54:55], v[56:57], 2, v[54:55]
	v_bfe_i32 v56, v97, 0, 1
	v_ashrrev_i32_e32 v20, 8, v20
	v_and_b32_e32 v56, 0x3000, v56
	v_mov_b32_e32 v57, v67
	v_mul_hi_i32 v21, v20, s6
	v_lshl_add_u64 v[54:55], v[54:55], 0, v[56:57]
	v_add_u32_e32 v56, 0x1a00, v1
	v_lshrrev_b32_e32 v26, 31, v21
	v_ashrrev_i32_e32 v21, 1, v21
	v_ashrrev_i32_e32 v56, 8, v56
	v_add_u32_e32 v87, v21, v26
	v_mul_hi_i32 v57, v56, s6
	v_lshl_add_u32 v21, v87, 3, v87
	v_lshrrev_b32_e32 v58, 31, v57
	v_ashrrev_i32_e32 v57, 1, v57
	v_lshl_add_u64 v[6:7], v[6:7], 0, v[66:67]
	v_lshl_add_u64 v[8:9], v[8:9], 0, v[66:67]
	v_sub_u32_e32 v80, v20, v21
	v_ashrrev_i32_e32 v20, 1, v87
	v_add_u32_e32 v99, v57, v58
	global_load_dwordx4 v[22:25], v[6:7], off
	s_nop 0
	global_load_dwordx4 v[6:9], v[8:9], off
	v_lshl_add_u32 v20, v20, 3, v20
	v_mul_lo_u32 v26, v80, s5
	v_lshl_add_u32 v57, v99, 3, v99
	v_mad_i64_i32 v[20:21], s[10:11], v20, s1, v[50:51]
	v_ashrrev_i32_e32 v27, 31, v26
	v_sub_u32_e32 v92, v56, v57
	v_ashrrev_i32_e32 v56, 1, v99
	v_lshl_add_u64 v[20:21], v[26:27], 2, v[20:21]
	v_bfe_i32 v26, v87, 0, 1
	v_lshl_add_u32 v56, v56, 3, v56
	v_mul_lo_u32 v58, v92, s5
	v_and_b32_e32 v26, 0x3000, v26
	v_mov_b32_e32 v27, v67
	v_mad_i64_i32 v[56:57], s[10:11], v56, s1, v[50:51]
	v_ashrrev_i32_e32 v59, 31, v58
	v_lshl_add_u64 v[20:21], v[20:21], 0, v[26:27]
	v_add_u32_e32 v26, 0x1000, v1
	v_lshl_add_u64 v[56:57], v[58:59], 2, v[56:57]
	v_bfe_i32 v58, v99, 0, 1
	v_ashrrev_i32_e32 v26, 8, v26
	v_and_b32_e32 v58, 0x3000, v58
	v_mov_b32_e32 v59, v67
	v_mul_hi_i32 v27, v26, s6
	v_lshl_add_u64 v[56:57], v[56:57], 0, v[58:59]
	v_add_u32_e32 v58, 0x1c00, v1
	v_lshrrev_b32_e32 v28, 31, v27
	v_ashrrev_i32_e32 v27, 1, v27
	v_ashrrev_i32_e32 v58, 8, v58
	v_add_u32_e32 v89, v27, v28
	v_mul_hi_i32 v59, v58, s6
	v_lshl_add_u32 v27, v89, 3, v89
	v_lshrrev_b32_e32 v60, 31, v59
	v_ashrrev_i32_e32 v59, 1, v59
	v_sub_u32_e32 v82, v26, v27
	v_ashrrev_i32_e32 v26, 1, v89
	v_add_u32_e32 v106, v59, v60
	v_lshl_add_u32 v26, v26, 3, v26
	v_mul_lo_u32 v28, v82, s5
	v_lshl_add_u32 v59, v106, 3, v106
	v_mad_i64_i32 v[26:27], s[10:11], v26, s1, v[50:51]
	v_ashrrev_i32_e32 v29, 31, v28
	v_sub_u32_e32 v94, v58, v59
	v_ashrrev_i32_e32 v58, 1, v106
	v_lshl_add_u64 v[26:27], v[28:29], 2, v[26:27]
	v_bfe_i32 v28, v89, 0, 1
	v_lshl_add_u32 v58, v58, 3, v58
	v_mul_lo_u32 v60, v94, s5
	v_and_b32_e32 v28, 0x3000, v28
	v_mov_b32_e32 v29, v67
	v_mad_i64_i32 v[58:59], s[10:11], v58, s1, v[50:51]
	v_ashrrev_i32_e32 v61, 31, v60
	v_lshl_add_u64 v[26:27], v[26:27], 0, v[28:29]
	v_add_u32_e32 v28, 0x1200, v1
	v_lshl_add_u64 v[58:59], v[60:61], 2, v[58:59]
	v_bfe_i32 v60, v106, 0, 1
	v_ashrrev_i32_e32 v28, 8, v28
	v_and_b32_e32 v60, 0x3000, v60
	v_mov_b32_e32 v61, v67
	v_lshl_add_u64 v[18:19], v[18:19], 0, v[66:67]
	v_lshl_add_u64 v[20:21], v[20:21], 0, v[66:67]
	v_mul_hi_i32 v29, v28, s6
	v_lshl_add_u64 v[58:59], v[58:59], 0, v[60:61]
	v_add_u32_e32 v60, 0x1e00, v1
	global_load_dwordx4 v[30:33], v[18:19], off
	s_nop 0
	global_load_dwordx4 v[18:21], v[20:21], off
	v_lshrrev_b32_e32 v34, 31, v29
	v_ashrrev_i32_e32 v29, 1, v29
	v_ashrrev_i32_e32 v60, 8, v60
	v_add_u32_e32 v91, v29, v34
	v_mul_hi_i32 v61, v60, s6
	v_lshl_add_u32 v29, v91, 3, v91
	v_lshrrev_b32_e32 v62, 31, v61
	v_ashrrev_i32_e32 v61, 1, v61
	v_sub_u32_e32 v84, v28, v29
	v_ashrrev_i32_e32 v28, 1, v91
	v_add_u32_e32 v107, v61, v62
	v_lshl_add_u32 v28, v28, 3, v28
	v_mul_lo_u32 v34, v84, s5
	v_lshl_add_u32 v61, v107, 3, v107
	v_mad_i64_i32 v[28:29], s[10:11], v28, s1, v[50:51]
	v_ashrrev_i32_e32 v35, 31, v34
	v_sub_u32_e32 v96, v60, v61
	v_ashrrev_i32_e32 v60, 1, v107
	v_lshl_add_u64 v[28:29], v[34:35], 2, v[28:29]
	v_bfe_i32 v34, v91, 0, 1
	v_lshl_add_u32 v60, v60, 3, v60
	v_mul_lo_u32 v62, v96, s5
	v_and_b32_e32 v34, 0x3000, v34
	v_mov_b32_e32 v35, v67
	v_mad_i64_i32 v[60:61], s[10:11], v60, s1, v[50:51]
	v_ashrrev_i32_e32 v63, 31, v62
	v_lshl_add_u64 v[28:29], v[28:29], 0, v[34:35]
	v_add_u32_e32 v34, 0x1400, v1
	v_lshl_add_u64 v[60:61], v[62:63], 2, v[60:61]
	v_bfe_i32 v62, v107, 0, 1
	v_ashrrev_i32_e32 v34, 8, v34
	v_and_b32_e32 v62, 0x3000, v62
	v_mov_b32_e32 v63, v67
	v_mul_hi_i32 v35, v34, s6
	v_lshl_add_u64 v[60:61], v[60:61], 0, v[62:63]
	v_add_u32_e32 v62, 0x2000, v1
	v_lshrrev_b32_e32 v36, 31, v35
	v_ashrrev_i32_e32 v35, 1, v35
	v_ashrrev_i32_e32 v62, 8, v62
	v_add_u32_e32 v93, v35, v36
	v_mul_hi_i32 v63, v62, s6
	v_lshl_add_u32 v35, v93, 3, v93
	v_lshrrev_b32_e32 v64, 31, v63
	v_ashrrev_i32_e32 v63, 1, v63
	v_sub_u32_e32 v86, v34, v35
	v_ashrrev_i32_e32 v34, 1, v93
	v_add_u32_e32 v108, v63, v64
	v_lshl_add_u32 v34, v34, 3, v34
	v_mul_lo_u32 v36, v86, s5
	v_lshl_add_u32 v63, v108, 3, v108
	v_mad_i64_i32 v[34:35], s[10:11], v34, s1, v[50:51]
	v_ashrrev_i32_e32 v37, 31, v36
	v_sub_u32_e32 v98, v62, v63
	v_ashrrev_i32_e32 v62, 1, v108
	v_lshl_add_u64 v[26:27], v[26:27], 0, v[66:67]
	v_lshl_add_u64 v[28:29], v[28:29], 0, v[66:67]
	v_lshl_add_u64 v[34:35], v[36:37], 2, v[34:35]
	v_bfe_i32 v36, v93, 0, 1
	v_lshl_add_u32 v62, v62, 3, v62
	v_mul_lo_u32 v64, v98, s5
	global_load_dwordx4 v[42:45], v[26:27], off
	s_nop 0
	global_load_dwordx4 v[26:29], v[28:29], off
	v_and_b32_e32 v36, 0x3000, v36
	v_mov_b32_e32 v37, v67
	v_mad_i64_i32 v[62:63], s[10:11], v62, s1, v[50:51]
	v_ashrrev_i32_e32 v65, 31, v64
	v_lshl_add_u64 v[34:35], v[34:35], 0, v[36:37]
	v_add_u32_e32 v36, 0x1600, v1
	v_lshl_add_u64 v[62:63], v[64:65], 2, v[62:63]
	v_bfe_i32 v64, v108, 0, 1
	v_ashrrev_i32_e32 v36, 8, v36
	v_and_b32_e32 v64, 0x3000, v64
	v_mov_b32_e32 v65, v67
	v_mul_hi_i32 v37, v36, s6
	v_lshl_add_u64 v[100:101], v[62:63], 0, v[64:65]
	v_add_u32_e32 v62, 0x2200, v1
	v_lshrrev_b32_e32 v46, 31, v37
	v_ashrrev_i32_e32 v37, 1, v37
	v_ashrrev_i32_e32 v104, 8, v62
	v_add_u32_e32 v95, v37, v46
	v_mul_hi_i32 v62, v104, s6
	v_lshl_add_u32 v37, v95, 3, v95
	v_lshrrev_b32_e32 v63, 31, v62
	v_ashrrev_i32_e32 v62, 1, v62
	v_sub_u32_e32 v88, v36, v37
	v_ashrrev_i32_e32 v36, 1, v95
	v_add_u32_e32 v109, v62, v63
	s_waitcnt vmcnt(9)
	v_bfe_u32 v62, v38, 16, 1
	s_movk_i32 s6, 0x7fff
	v_lshl_add_u32 v36, v36, 3, v36
	v_mul_lo_u32 v46, v88, s5
	v_add3_u32 v102, v38, v62, s6
	v_bfe_u32 v38, v39, 16, 1
	v_mad_i64_i32 v[36:37], s[10:11], v36, s1, v[50:51]
	v_ashrrev_i32_e32 v47, 31, v46
	v_add3_u32 v103, v39, v38, s6
	v_bfe_u32 v38, v40, 16, 1
	v_mad_u64_u32 v[52:53], s[10:11], v53, 10, v[52:53]
	v_lshl_add_u64 v[36:37], v[46:47], 2, v[36:37]
	v_bfe_i32 v46, v95, 0, 1
	v_add3_u32 v105, v40, v38, s6
	v_bfe_u32 v38, v41, 16, 1
	s_waitcnt vmcnt(8)
	v_bfe_u32 v53, v10, 16, 1
	v_and_b32_e32 v46, 0x3000, v46
	v_mov_b32_e32 v47, v67
	v_add3_u32 v110, v41, v38, s6
	v_lshl_add_u64 v[38:39], v[58:59], 0, v[66:67]
	v_lshrrev_b32_e32 v58, 16, v102
	s_mov_b32 s7, 0xffff0000
	s_movk_i32 s12, 0x810
	v_add3_u32 v53, v10, v53, s6
	v_bfe_u32 v10, v11, 16, 1
	v_lshl_add_u64 v[36:37], v[36:37], 0, v[46:47]
	v_and_or_b32 v102, v103, s7, v58
	v_lshrrev_b32_e32 v58, 16, v105
	v_mul_lo_u32 v52, v52, s12
	v_add3_u32 v105, v11, v10, s6
	v_bfe_u32 v10, v12, 16, 1
	v_lshlrev_b32_e32 v73, 1, v73
	v_lshl_add_u64 v[34:35], v[34:35], 0, v[66:67]
	v_lshl_add_u64 v[36:37], v[36:37], 0, v[66:67]
	v_lshl_add_u64 v[54:55], v[54:55], 0, v[66:67]
	v_lshl_add_u64 v[56:57], v[56:57], 0, v[66:67]
	v_lshl_add_u64 v[40:41], v[60:61], 0, v[66:67]
	v_and_or_b32 v103, v110, s7, v58
	v_add3_u32 v110, v12, v10, s6
	v_add3_u32 v12, 0, v52, v73
	global_load_dwordx4 v[46:49], v[34:35], off
	s_nop 0
	global_load_dwordx4 v[34:37], v[36:37], off
	s_nop 0
	global_load_dwordx4 v[62:65], v[54:55], off
	s_nop 0
	global_load_dwordx4 v[54:57], v[56:57], off
	v_bfe_u32 v10, v13, 16, 1
	global_load_dwordx4 v[58:61], v[38:39], off
	s_nop 0
	global_load_dwordx4 v[38:41], v[40:41], off
	ds_write_b64 v12, v[102:103]
	v_lshl_add_u32 v12, v109, 3, v109
	v_add3_u32 v111, v13, v10, s6
	v_lshl_add_u64 v[10:11], v[100:101], 0, v[66:67]
	v_sub_u32_e32 v100, v104, v12
	v_ashrrev_i32_e32 v12, 1, v109
	v_lshl_add_u32 v12, v12, 3, v12
	v_mad_i64_i32 v[12:13], s[10:11], v12, s1, v[50:51]
	v_mul_lo_u32 v50, v100, s5
	v_ashrrev_i32_e32 v51, 31, v50
	v_lshl_add_u64 v[12:13], v[50:51], 2, v[12:13]
	v_bfe_i32 v50, v109, 0, 1
	v_and_b32_e32 v50, 0x3000, v50
	v_mov_b32_e32 v51, v67
	v_lshl_add_u64 v[12:13], v[12:13], 0, v[50:51]
	v_lshrrev_b32_e32 v50, 16, v53
	v_and_or_b32 v102, v105, s7, v50
	v_mad_u64_u32 v[104:105], s[10:11], v75, 10, v[68:69]
	v_lshl_add_u64 v[12:13], v[12:13], 0, v[66:67]
	v_lshrrev_b32_e32 v50, 16, v110
	v_mul_lo_u32 v66, v104, s12
	v_and_or_b32 v103, v111, s7, v50
	v_add3_u32 v66, 0, v66, v73
	global_load_dwordx4 v[50:53], v[10:11], off
	s_nop 0
	global_load_dwordx4 v[10:13], v[12:13], off
	ds_write_b64 v66, v[102:103]
	s_waitcnt vmcnt(15)
	v_bfe_u32 v66, v14, 16, 1
	v_add3_u32 v14, v14, v66, s6
	v_bfe_u32 v66, v15, 16, 1
	v_lshrrev_b32_e32 v14, 16, v14
	v_add3_u32 v15, v15, v66, s6
	v_and_or_b32 v14, v15, s7, v14
	v_bfe_u32 v15, v16, 16, 1
	v_add3_u32 v15, v16, v15, s6
	v_bfe_u32 v16, v17, 16, 1
	v_lshrrev_b32_e32 v15, 16, v15
	v_add3_u32 v16, v17, v16, s6
	v_and_or_b32 v15, v16, s7, v15
	v_mad_u64_u32 v[16:17], s[10:11], v77, 10, v[70:71]
	v_mul_lo_u32 v16, v16, s12
	v_add3_u32 v16, 0, v16, v73
	ds_write_b64 v16, v[14:15]
	s_waitcnt vmcnt(14)
	v_bfe_u32 v14, v2, 16, 1
	v_add3_u32 v2, v2, v14, s6
	v_bfe_u32 v14, v3, 16, 1
	v_lshrrev_b32_e32 v2, 16, v2
	v_add3_u32 v3, v3, v14, s6
	v_and_or_b32 v2, v3, s7, v2
	v_bfe_u32 v3, v4, 16, 1
	v_add3_u32 v3, v4, v3, s6
	v_bfe_u32 v4, v5, 16, 1
	v_lshrrev_b32_e32 v3, 16, v3
	v_add3_u32 v4, v5, v4, s6
	v_and_or_b32 v3, v4, s7, v3
	v_mad_u64_u32 v[4:5], s[10:11], v79, 10, v[72:73]
	v_mul_lo_u32 v4, v4, s12
	v_add3_u32 v4, 0, v4, v73
	ds_write_b64 v4, v[2:3]
	s_waitcnt vmcnt(13)
	v_bfe_u32 v2, v22, 16, 1
	v_add3_u32 v2, v22, v2, s6
	v_bfe_u32 v3, v23, 16, 1
	v_lshrrev_b32_e32 v2, 16, v2
	v_add3_u32 v3, v23, v3, s6
	v_and_or_b32 v2, v3, s7, v2
	v_bfe_u32 v3, v24, 16, 1
	v_add3_u32 v3, v24, v3, s6
	v_bfe_u32 v4, v25, 16, 1
	v_lshrrev_b32_e32 v3, 16, v3
	v_add3_u32 v4, v25, v4, s6
	v_and_or_b32 v3, v4, s7, v3
	v_mad_u64_u32 v[4:5], s[10:11], v81, 10, v[74:75]
	v_mul_lo_u32 v4, v4, s12
	v_add3_u32 v4, 0, v4, v73
	ds_write_b64 v4, v[2:3]
	s_waitcnt vmcnt(12)
	v_bfe_u32 v2, v6, 16, 1
	v_add3_u32 v2, v6, v2, s6
	v_bfe_u32 v3, v7, 16, 1
	v_lshrrev_b32_e32 v2, 16, v2
	v_add3_u32 v3, v7, v3, s6
	v_and_or_b32 v2, v3, s7, v2
	v_bfe_u32 v3, v8, 16, 1
	v_add3_u32 v3, v8, v3, s6
	v_bfe_u32 v4, v9, 16, 1
	v_lshrrev_b32_e32 v3, 16, v3
	v_add3_u32 v4, v9, v4, s6
	v_and_or_b32 v3, v4, s7, v3
	v_mad_u64_u32 v[4:5], s[10:11], v83, 10, v[76:77]
	v_mul_lo_u32 v4, v4, s12
	v_add3_u32 v4, 0, v4, v73
	ds_write_b64 v4, v[2:3]
	s_waitcnt vmcnt(11)
	v_bfe_u32 v2, v30, 16, 1
	v_add3_u32 v2, v30, v2, s6
	v_bfe_u32 v3, v31, 16, 1
	v_lshrrev_b32_e32 v2, 16, v2
	v_add3_u32 v3, v31, v3, s6
	v_and_or_b32 v2, v3, s7, v2
	v_bfe_u32 v3, v32, 16, 1
	v_add3_u32 v3, v32, v3, s6
	v_bfe_u32 v4, v33, 16, 1
	v_lshrrev_b32_e32 v3, 16, v3
	v_add3_u32 v4, v33, v4, s6
	v_and_or_b32 v3, v4, s7, v3
	v_mad_u64_u32 v[4:5], s[10:11], v85, 10, v[78:79]
	v_mul_lo_u32 v4, v4, s12
	v_add3_u32 v4, 0, v4, v73
	ds_write_b64 v4, v[2:3]
	s_waitcnt vmcnt(10)
	v_bfe_u32 v2, v18, 16, 1
	v_add3_u32 v2, v18, v2, s6
	v_bfe_u32 v3, v19, 16, 1
	v_lshrrev_b32_e32 v2, 16, v2
	v_add3_u32 v3, v19, v3, s6
	v_and_or_b32 v2, v3, s7, v2
	v_bfe_u32 v3, v20, 16, 1
	v_add3_u32 v3, v20, v3, s6
	v_bfe_u32 v4, v21, 16, 1
	v_lshrrev_b32_e32 v3, 16, v3
	v_add3_u32 v4, v21, v4, s6
	v_and_or_b32 v3, v4, s7, v3
	v_mad_u64_u32 v[4:5], s[10:11], v87, 10, v[80:81]
	v_mul_lo_u32 v4, v4, s12
	v_add3_u32 v4, 0, v4, v73
	ds_write_b64 v4, v[2:3]
	s_waitcnt vmcnt(9)
	v_bfe_u32 v2, v42, 16, 1
	v_add3_u32 v2, v42, v2, s6
	v_bfe_u32 v3, v43, 16, 1
	v_lshrrev_b32_e32 v2, 16, v2
	v_add3_u32 v3, v43, v3, s6
	v_and_or_b32 v2, v3, s7, v2
	v_bfe_u32 v3, v44, 16, 1
	v_add3_u32 v3, v44, v3, s6
	v_bfe_u32 v4, v45, 16, 1
	v_lshrrev_b32_e32 v3, 16, v3
	v_add3_u32 v4, v45, v4, s6
	v_and_or_b32 v3, v4, s7, v3
	v_mad_u64_u32 v[4:5], s[10:11], v89, 10, v[82:83]
	v_mul_lo_u32 v4, v4, s12
	v_add3_u32 v4, 0, v4, v73
	ds_write_b64 v4, v[2:3]
	s_waitcnt vmcnt(8)
	v_bfe_u32 v2, v26, 16, 1
	v_add3_u32 v2, v26, v2, s6
	v_bfe_u32 v3, v27, 16, 1
	v_lshrrev_b32_e32 v2, 16, v2
	v_add3_u32 v3, v27, v3, s6
	v_and_or_b32 v2, v3, s7, v2
	v_bfe_u32 v3, v28, 16, 1
	v_add3_u32 v3, v28, v3, s6
	v_bfe_u32 v4, v29, 16, 1
	v_lshrrev_b32_e32 v3, 16, v3
	v_add3_u32 v4, v29, v4, s6
	v_and_or_b32 v3, v4, s7, v3
	v_mad_u64_u32 v[4:5], s[10:11], v91, 10, v[84:85]
	v_mul_lo_u32 v4, v4, s12
	v_add3_u32 v4, 0, v4, v73
	ds_write_b64 v4, v[2:3]
	s_waitcnt vmcnt(7)
	v_bfe_u32 v2, v46, 16, 1
	v_add3_u32 v2, v46, v2, s6
	v_bfe_u32 v3, v47, 16, 1
	v_lshrrev_b32_e32 v2, 16, v2
	v_add3_u32 v3, v47, v3, s6
	v_and_or_b32 v2, v3, s7, v2
	v_bfe_u32 v3, v48, 16, 1
	v_add3_u32 v3, v48, v3, s6
	v_bfe_u32 v4, v49, 16, 1
	v_lshrrev_b32_e32 v3, 16, v3
	v_add3_u32 v4, v49, v4, s6
	v_and_or_b32 v3, v4, s7, v3
	v_mad_u64_u32 v[4:5], s[10:11], v93, 10, v[86:87]
	v_mul_lo_u32 v4, v4, s12
	v_add3_u32 v4, 0, v4, v73
	ds_write_b64 v4, v[2:3]
	s_waitcnt vmcnt(6)
	v_bfe_u32 v2, v34, 16, 1
	v_add3_u32 v2, v34, v2, s6
	v_bfe_u32 v3, v35, 16, 1
	v_lshrrev_b32_e32 v2, 16, v2
	v_add3_u32 v3, v35, v3, s6
	v_and_or_b32 v2, v3, s7, v2
	v_bfe_u32 v3, v36, 16, 1
	v_add3_u32 v3, v36, v3, s6
	v_bfe_u32 v4, v37, 16, 1
	v_lshrrev_b32_e32 v3, 16, v3
	v_add3_u32 v4, v37, v4, s6
	v_and_or_b32 v3, v4, s7, v3
	v_mad_u64_u32 v[4:5], s[10:11], v95, 10, v[88:89]
	v_mul_lo_u32 v4, v4, s12
	v_add3_u32 v4, 0, v4, v73
	ds_write_b64 v4, v[2:3]
	s_waitcnt vmcnt(5)
	v_bfe_u32 v2, v62, 16, 1
	v_add3_u32 v2, v62, v2, s6
	v_bfe_u32 v3, v63, 16, 1
	v_lshrrev_b32_e32 v2, 16, v2
	v_add3_u32 v3, v63, v3, s6
	v_and_or_b32 v2, v3, s7, v2
	v_bfe_u32 v3, v64, 16, 1
	v_add3_u32 v3, v64, v3, s6
	v_bfe_u32 v4, v65, 16, 1
	v_lshrrev_b32_e32 v3, 16, v3
	v_add3_u32 v4, v65, v4, s6
	v_and_or_b32 v3, v4, s7, v3
	v_mad_u64_u32 v[4:5], s[10:11], v97, 10, v[90:91]
	v_mul_lo_u32 v4, v4, s12
	v_add3_u32 v4, 0, v4, v73
	ds_write_b64 v4, v[2:3]
	s_waitcnt vmcnt(4)
	v_bfe_u32 v2, v54, 16, 1
	v_add3_u32 v2, v54, v2, s6
	v_bfe_u32 v3, v55, 16, 1
	v_lshrrev_b32_e32 v2, 16, v2
	v_add3_u32 v3, v55, v3, s6
	v_and_or_b32 v2, v3, s7, v2
	v_bfe_u32 v3, v56, 16, 1
	v_add3_u32 v3, v56, v3, s6
	v_bfe_u32 v4, v57, 16, 1
	v_lshrrev_b32_e32 v3, 16, v3
	v_add3_u32 v4, v57, v4, s6
	v_and_or_b32 v3, v4, s7, v3
	v_mad_u64_u32 v[4:5], s[10:11], v99, 10, v[92:93]
	v_mul_lo_u32 v4, v4, s12
	v_add3_u32 v4, 0, v4, v73
	ds_write_b64 v4, v[2:3]
	s_waitcnt vmcnt(3)
	v_bfe_u32 v2, v58, 16, 1
	v_add3_u32 v2, v58, v2, s6
	v_bfe_u32 v3, v59, 16, 1
	v_lshrrev_b32_e32 v2, 16, v2
	v_add3_u32 v3, v59, v3, s6
	v_and_or_b32 v2, v3, s7, v2
	v_bfe_u32 v3, v60, 16, 1
	v_add3_u32 v3, v60, v3, s6
	v_bfe_u32 v4, v61, 16, 1
	v_lshrrev_b32_e32 v3, 16, v3
	v_add3_u32 v4, v61, v4, s6
	v_and_or_b32 v3, v4, s7, v3
	v_mad_u64_u32 v[4:5], s[10:11], v106, 10, v[94:95]
	v_mul_lo_u32 v4, v4, s12
	v_add3_u32 v4, 0, v4, v73
	ds_write_b64 v4, v[2:3]
	s_waitcnt vmcnt(2)
	v_bfe_u32 v2, v38, 16, 1
	v_add3_u32 v2, v38, v2, s6
	v_bfe_u32 v3, v39, 16, 1
	v_lshrrev_b32_e32 v2, 16, v2
	v_add3_u32 v3, v39, v3, s6
	v_and_or_b32 v2, v3, s7, v2
	v_bfe_u32 v3, v40, 16, 1
	v_add3_u32 v3, v40, v3, s6
	v_bfe_u32 v4, v41, 16, 1
	v_lshrrev_b32_e32 v3, 16, v3
	v_add3_u32 v4, v41, v4, s6
	v_and_or_b32 v3, v4, s7, v3
	v_mad_u64_u32 v[4:5], s[10:11], v107, 10, v[96:97]
	v_mul_lo_u32 v4, v4, s12
	v_add3_u32 v4, 0, v4, v73
	ds_write_b64 v4, v[2:3]
	s_waitcnt vmcnt(1)
	v_bfe_u32 v2, v50, 16, 1
	v_add3_u32 v2, v50, v2, s6
	v_bfe_u32 v3, v51, 16, 1
	v_lshrrev_b32_e32 v2, 16, v2
	v_add3_u32 v3, v51, v3, s6
	v_and_or_b32 v2, v3, s7, v2
	v_bfe_u32 v3, v52, 16, 1
	v_add3_u32 v3, v52, v3, s6
	v_bfe_u32 v4, v53, 16, 1
	v_lshrrev_b32_e32 v3, 16, v3
	v_add3_u32 v4, v53, v4, s6
	v_and_or_b32 v3, v4, s7, v3
	v_mad_u64_u32 v[4:5], s[10:11], v108, 10, v[98:99]
	v_mul_lo_u32 v4, v4, s12
	v_add3_u32 v4, 0, v4, v73
	ds_write_b64 v4, v[2:3]
	s_waitcnt vmcnt(0)
	v_bfe_u32 v2, v10, 16, 1
	v_add3_u32 v2, v10, v2, s6
	v_bfe_u32 v3, v11, 16, 1
	v_lshrrev_b32_e32 v2, 16, v2
	v_add3_u32 v3, v11, v3, s6
	v_and_or_b32 v2, v3, s7, v2
	v_bfe_u32 v3, v12, 16, 1
	v_add3_u32 v3, v12, v3, s6
	v_bfe_u32 v4, v13, 16, 1
	v_lshrrev_b32_e32 v3, 16, v3
	v_add3_u32 v4, v13, v4, s6
	v_and_or_b32 v3, v4, s7, v3
	v_mad_u64_u32 v[4:5], s[6:7], v109, 10, v[100:101]
	v_readfirstlane_b32 s0, v1
	v_mul_lo_u32 v4, v4, s12
	s_ashr_i32 s4, s0, 6
	s_mov_b32 s0, 0
	v_add3_u32 v4, 0, v4, v73
	ds_write_b64 v4, v[2:3]
	v_mul_i32_i24_e32 v2, 0x50a0, v69
	s_mov_b32 s1, s0
	v_add3_u32 v2, 0, v2, v73
	v_mov_b64_e32 v[4:5], s[0:1]
	ds_write_b64 v2, v[4:5] offset:18576
	v_mul_i32_i24_e32 v2, 0x50a0, v71
	s_add_i32 s13, s4, s90
	s_movk_i32 s8, 0x600
	v_add3_u32 v2, 0, v2, v73
	s_cmpk_gt_i32 s13, 0xbf
	ds_write_b64 v2, v[4:5] offset:18576
	s_waitcnt lgkmcnt(0)
	s_barrier
	s_cbranch_scc1 .LBB0_130
	v_and_b32_e32 v6, 15, v1
	v_bfe_u32 v1, v1, 4, 2
	v_lshlrev_b32_e32 v3, 2, v1
	v_lshlrev_b32_e32 v66, 4, v1
	v_cmp_ne_u32_e32 vcc, 3, v1
	v_mul_u32_u24_e32 v2, 0x1800, v1
	v_or_b32_e32 v1, 1, v3
	v_or_b32_e32 v5, 2, v3
	v_or_b32_e32 v3, 3, v3
	v_cmp_gt_u32_e64 s[4:5], 9, v3
	v_mov_b32_e32 v3, 0xc00
	s_add_u32 s14, s34, 0xbc00000
	v_mul_u32_u24_e32 v4, 0x600, v1
	v_mad_u32_u24 v18, v1, s8, s8
	v_mad_u32_u24 v20, v1, s8, v3
	v_lshl_add_u64 v[12:13], s[34:35], 0, v[66:67]
	s_mov_b64 s[8:9], 0x200100
	v_min_u32_e32 v8, 9, v6
	v_add_u32_e32 v10, 0, v66
	s_addc_u32 s15, s35, 0
	v_cmp_gt_u32_e64 s[0:1], 9, v1
	v_cmp_gt_u32_e64 s[6:7], 9, v5
	v_lshl_add_u64 v[12:13], v[12:13], 0, s[8:9]
	s_mov_b64 s[8:9], 0x200
	v_lshlrev_b32_e32 v66, 2, v6
	v_lshlrev_b32_e32 v14, 2, v2
	v_lshlrev_b32_e32 v16, 2, v4
	v_lshlrev_b32_e32 v18, 2, v18
	v_lshlrev_b32_e32 v20, 2, v20
	v_mov_b32_e32 v1, 0x300000
	s_branch .LBB0_120
